# speedup vs baseline: 1.0023x; 1.0023x over previous
; __device__ __forceinline__ void topk_row(const Params& p, int r, int lane, __attribute__((address_space(3))) int* out) {
;   {
;     const int t = r & (L - 1), n = t + 1;
;     const float* sc = p.SC + (size_t)r * L;
;     const int nch = (n + 63) >> 6;
;     int lo = lane;
;     asm volatile("" : "+v"(lo));
;     unsigned key[128];
;     const float* scl = sc + lo;
; #pragma unroll
;     for (int i = 0; i < 128; ++i) {
;       const int ic = min(i, nch - 1);
;       key[i] = __float_as_uint(scl[ic * 64]);
;     }
.LBB0_71:
	s_andn2_b64 vcc, exec, s[0:1]
	s_cbranch_vccnz .LBB0_902
	v_readlane_b32 s0, v244, 0
	v_readlane_b32 s1, v244, 1
	s_ashr_i32 s1, s0, 31
	v_writelane_b32 v244, s0, 0
	v_readlane_b32 s16, v246, 0
	v_readlane_b32 s18, v246, 2
	v_writelane_b32 v244, s1, 1
	s_lshl_b64 s[0:1], s[0:1], 15
	v_readlane_b32 s19, v246, 3
	s_add_u32 s0, s18, s0
	s_addc_u32 s1, s19, s1
	s_add_i32 s4, s15, 64
	v_mov_b32_e32 v0, v218
	s_waitcnt lgkmcnt(0)
	s_lshr_b32 s4, s4, 6
	v_readlane_b32 s17, v246, 1
	v_ashrrev_i32_e32 v1, 31, v0
	v_lshl_add_u64 v[2:3], v[0:1], 2, s[0:1]
	s_add_i32 s0, s4, -1
	s_min_u32 s1, s0, 5
	s_lshl_b32 s4, s1, 8
	s_min_u32 s1, s0, 6
	v_lshl_add_u64 v[10:11], v[2:3], 0, s[4:5]
	s_lshl_b32 s4, s1, 8
	s_min_u32 s1, s0, 7
	global_load_dword v9, v[2:3], off nt
	global_load_dword v8, v[2:3], off offset:256 nt
	global_load_dword v7, v[2:3], off offset:512 nt
	global_load_dword v4, v[2:3], off offset:768 nt
	global_load_dword v1, v[2:3], off offset:1024 nt
	global_load_dword v5, v[10:11], off nt
	v_lshl_add_u64 v[10:11], v[2:3], 0, s[4:5]
	s_lshl_b32 s4, s1, 8
	s_min_u32 s1, s0, 8
	global_load_dword v6, v[10:11], off nt
	v_lshl_add_u64 v[10:11], v[2:3], 0, s[4:5]
	s_lshl_b32 s4, s1, 8
	s_min_u32 s1, s0, 9
	v_lshl_add_u64 v[12:13], v[2:3], 0, s[4:5]
	s_lshl_b32 s4, s1, 8
	s_min_u32 s1, s0, 10
	global_load_dword v11, v[10:11], off nt
	s_nop 0
	global_load_dword v10, v[12:13], off nt
	v_lshl_add_u64 v[12:13], v[2:3], 0, s[4:5]
	s_lshl_b32 s4, s1, 8
	s_min_u32 s1, s0, 11
	v_lshl_add_u64 v[14:15], v[2:3], 0, s[4:5]
	s_lshl_b32 s4, s1, 8
	s_min_u32 s1, s0, 12
	global_load_dword v12, v[12:13], off nt
	s_nop 0
	global_load_dword v13, v[14:15], off nt
	v_lshl_add_u64 v[14:15], v[2:3], 0, s[4:5]
	s_lshl_b32 s4, s1, 8
	s_min_u32 s1, s0, 13
	v_lshl_add_u64 v[16:17], v[2:3], 0, s[4:5]
	s_lshl_b32 s4, s1, 8
	s_min_u32 s1, s0, 14
	global_load_dword v14, v[14:15], off nt
	s_nop 0
	global_load_dword v15, v[16:17], off nt
	v_lshl_add_u64 v[16:17], v[2:3], 0, s[4:5]
	s_lshl_b32 s4, s1, 8
	s_min_u32 s1, s0, 15
	v_lshl_add_u64 v[18:19], v[2:3], 0, s[4:5]
	s_lshl_b32 s4, s1, 8
	s_min_u32 s1, s0, 16
	global_load_dword v16, v[16:17], off nt
	s_nop 0
	global_load_dword v17, v[18:19], off nt
	v_lshl_add_u64 v[18:19], v[2:3], 0, s[4:5]
	s_lshl_b32 s4, s1, 8
	s_min_u32 s1, s0, 17
	v_lshl_add_u64 v[20:21], v[2:3], 0, s[4:5]
	s_lshl_b32 s4, s1, 8
	s_min_u32 s1, s0, 18
	global_load_dword v19, v[18:19], off nt
	s_nop 0
	global_load_dword v18, v[20:21], off nt
	v_lshl_add_u64 v[20:21], v[2:3], 0, s[4:5]
	s_lshl_b32 s4, s1, 8
	s_min_u32 s1, s0, 19
	v_lshl_add_u64 v[22:23], v[2:3], 0, s[4:5]
	s_lshl_b32 s4, s1, 8
	s_min_u32 s1, s0, 20
	global_load_dword v20, v[20:21], off nt
	s_nop 0
	global_load_dword v21, v[22:23], off nt
	v_lshl_add_u64 v[22:23], v[2:3], 0, s[4:5]
	s_lshl_b32 s4, s1, 8
	s_min_u32 s1, s0, 21
	v_lshl_add_u64 v[24:25], v[2:3], 0, s[4:5]
	s_lshl_b32 s4, s1, 8
	s_min_u32 s1, s0, 22
	global_load_dword v22, v[22:23], off nt
	s_nop 0
	global_load_dword v23, v[24:25], off nt
	v_lshl_add_u64 v[24:25], v[2:3], 0, s[4:5]
	s_lshl_b32 s4, s1, 8
	s_min_u32 s1, s0, 23
	v_lshl_add_u64 v[26:27], v[2:3], 0, s[4:5]
	s_lshl_b32 s4, s1, 8
	s_min_u32 s1, s0, 24
	global_load_dword v24, v[24:25], off nt
	s_nop 0
	global_load_dword v25, v[26:27], off nt
	v_lshl_add_u64 v[26:27], v[2:3], 0, s[4:5]
	s_lshl_b32 s4, s1, 8
	s_min_u32 s1, s0, 25
	v_lshl_add_u64 v[28:29], v[2:3], 0, s[4:5]
	s_lshl_b32 s4, s1, 8
	s_min_u32 s1, s0, 26
	global_load_dword v27, v[26:27], off nt
	s_nop 0
	global_load_dword v26, v[28:29], off nt
	v_lshl_add_u64 v[28:29], v[2:3], 0, s[4:5]
	s_lshl_b32 s4, s1, 8
	s_min_u32 s1, s0, 27
	v_lshl_add_u64 v[30:31], v[2:3], 0, s[4:5]
	s_lshl_b32 s4, s1, 8
	s_min_u32 s1, s0, 28
	global_load_dword v28, v[28:29], off nt
	s_nop 0
	global_load_dword v29, v[30:31], off nt
	v_lshl_add_u64 v[30:31], v[2:3], 0, s[4:5]
	s_lshl_b32 s4, s1, 8
	s_min_u32 s1, s0, 29
	v_lshl_add_u64 v[34:35], v[2:3], 0, s[4:5]
	s_lshl_b32 s4, s1, 8
	s_min_u32 s1, s0, 30
	global_load_dword v30, v[30:31], off nt
	s_nop 0
	global_load_dword v31, v[34:35], off nt
	v_lshl_add_u64 v[34:35], v[2:3], 0, s[4:5]
	s_lshl_b32 s4, s1, 8
	s_min_u32 s1, s0, 31
	global_load_dword v32, v[34:35], off nt
	v_lshl_add_u64 v[34:35], v[2:3], 0, s[4:5]
	s_lshl_b32 s4, s1, 8
	s_min_u32 s1, s0, 32
	v_lshl_add_u64 v[36:37], v[2:3], 0, s[4:5]
	s_lshl_b32 s4, s1, 8
	s_min_u32 s1, s0, 33
	v_lshl_add_u64 v[38:39], v[2:3], 0, s[4:5]
	s_lshl_b32 s4, s1, 8
	s_min_u32 s1, s0, 34
	global_load_dword v34, v[34:35], off nt
	s_nop 0
	global_load_dword v36, v[36:37], off nt
	s_nop 0
	global_load_dword v35, v[38:39], off nt
	v_lshl_add_u64 v[38:39], v[2:3], 0, s[4:5]
	s_lshl_b32 s4, s1, 8
	s_min_u32 s1, s0, 35
	global_load_dword v37, v[38:39], off nt
	v_lshl_add_u64 v[38:39], v[2:3], 0, s[4:5]
	s_lshl_b32 s4, s1, 8
	s_min_u32 s1, s0, 36
	v_lshl_add_u64 v[40:41], v[2:3], 0, s[4:5]
	s_lshl_b32 s4, s1, 8
	s_min_u32 s1, s0, 37
	global_load_dword v38, v[38:39], off nt
	s_nop 0
	global_load_dword v39, v[40:41], off nt
	v_lshl_add_u64 v[40:41], v[2:3], 0, s[4:5]
	s_lshl_b32 s4, s1, 8
	s_min_u32 s1, s0, 38
	v_lshl_add_u64 v[42:43], v[2:3], 0, s[4:5]
	s_lshl_b32 s4, s1, 8
	s_min_u32 s1, s0, 39
	global_load_dword v40, v[40:41], off nt
	s_nop 0
	global_load_dword v41, v[42:43], off nt
	v_lshl_add_u64 v[42:43], v[2:3], 0, s[4:5]
	s_lshl_b32 s4, s1, 8
	s_min_u32 s1, s0, 40
	v_lshl_add_u64 v[44:45], v[2:3], 0, s[4:5]
	s_lshl_b32 s4, s1, 8
	s_min_u32 s1, s0, 41
	v_lshl_add_u64 v[46:47], v[2:3], 0, s[4:5]
	s_lshl_b32 s4, s1, 8
	s_min_u32 s1, s0, 42
	global_load_dword v42, v[42:43], off nt
	s_nop 0
	global_load_dword v44, v[44:45], off nt
	s_nop 0
; __device__ __forceinline__ void topk_row(const Params& p, int r, int lane, __attribute__((address_space(3))) int* out) {
;     ...
; #pragma unroll
;     for (int i = 0; i < 128; ++i) {
;       const int ic = min(i, nch - 1);
;       key[i] = __float_as_uint(scl[ic * 64]);
;     }
	global_load_dword v43, v[46:47], off nt
	v_lshl_add_u64 v[46:47], v[2:3], 0, s[4:5]
	s_lshl_b32 s4, s1, 8
	s_min_u32 s1, s0, 43
	global_load_dword v45, v[46:47], off nt
	v_lshl_add_u64 v[46:47], v[2:3], 0, s[4:5]
	s_lshl_b32 s4, s1, 8
	s_min_u32 s1, s0, 44
	v_lshl_add_u64 v[48:49], v[2:3], 0, s[4:5]
	s_lshl_b32 s4, s1, 8
	s_min_u32 s1, s0, 45
	global_load_dword v46, v[46:47], off nt
	s_nop 0
	global_load_dword v47, v[48:49], off nt
	v_lshl_add_u64 v[48:49], v[2:3], 0, s[4:5]
	s_lshl_b32 s4, s1, 8
	s_min_u32 s1, s0, 46
	v_lshl_add_u64 v[50:51], v[2:3], 0, s[4:5]
	s_lshl_b32 s4, s1, 8
	s_min_u32 s1, s0, 47
	global_load_dword v48, v[48:49], off nt
	s_nop 0
	global_load_dword v49, v[50:51], off nt
	v_lshl_add_u64 v[50:51], v[2:3], 0, s[4:5]
	s_lshl_b32 s4, s1, 8
	s_min_u32 s1, s0, 48
	v_lshl_add_u64 v[52:53], v[2:3], 0, s[4:5]
	s_lshl_b32 s4, s1, 8
	s_min_u32 s1, s0, 49
	v_lshl_add_u64 v[54:55], v[2:3], 0, s[4:5]
	s_lshl_b32 s4, s1, 8
	s_min_u32 s1, s0, 50
	global_load_dword v50, v[50:51], off nt
	s_nop 0
	global_load_dword v52, v[52:53], off nt
	s_nop 0
	global_load_dword v51, v[54:55], off nt
	v_lshl_add_u64 v[54:55], v[2:3], 0, s[4:5]
	s_lshl_b32 s4, s1, 8
	s_min_u32 s1, s0, 51
	global_load_dword v53, v[54:55], off nt
	v_lshl_add_u64 v[54:55], v[2:3], 0, s[4:5]
	s_lshl_b32 s4, s1, 8
	s_min_u32 s1, s0, 52
	v_lshl_add_u64 v[56:57], v[2:3], 0, s[4:5]
	s_lshl_b32 s4, s1, 8
	s_min_u32 s1, s0, 53
	global_load_dword v54, v[54:55], off nt
	s_nop 0
	global_load_dword v55, v[56:57], off nt
	v_lshl_add_u64 v[56:57], v[2:3], 0, s[4:5]
	s_lshl_b32 s4, s1, 8
	s_min_u32 s1, s0, 54
	v_lshl_add_u64 v[58:59], v[2:3], 0, s[4:5]
	s_lshl_b32 s4, s1, 8
	s_min_u32 s1, s0, 55
	global_load_dword v56, v[56:57], off nt
	s_nop 0
	global_load_dword v57, v[58:59], off nt
	v_lshl_add_u64 v[58:59], v[2:3], 0, s[4:5]
	s_lshl_b32 s4, s1, 8
	s_min_u32 s1, s0, 56
	v_lshl_add_u64 v[60:61], v[2:3], 0, s[4:5]
	s_lshl_b32 s4, s1, 8
	s_min_u32 s1, s0, 57
	v_lshl_add_u64 v[62:63], v[2:3], 0, s[4:5]
	s_lshl_b32 s4, s1, 8
	s_min_u32 s1, s0, 58
	global_load_dword v58, v[58:59], off nt
	s_nop 0
	global_load_dword v60, v[60:61], off nt
	s_nop 0
	global_load_dword v59, v[62:63], off nt
	v_lshl_add_u64 v[62:63], v[2:3], 0, s[4:5]
	s_lshl_b32 s4, s1, 8
	s_min_u32 s1, s0, 59
	global_load_dword v61, v[62:63], off nt
	v_lshl_add_u64 v[62:63], v[2:3], 0, s[4:5]
	s_lshl_b32 s4, s1, 8
	s_min_u32 s1, s0, 60
	v_lshl_add_u64 v[64:65], v[2:3], 0, s[4:5]
	s_lshl_b32 s4, s1, 8
	s_min_u32 s1, s0, 61
	global_load_dword v62, v[62:63], off nt
	s_nop 0
	global_load_dword v63, v[64:65], off nt
	v_lshl_add_u64 v[64:65], v[2:3], 0, s[4:5]
	s_lshl_b32 s4, s1, 8
	s_min_u32 s1, s0, 62
	v_lshl_add_u64 v[66:67], v[2:3], 0, s[4:5]
	s_lshl_b32 s4, s1, 8
	s_min_u32 s1, s0, 63
	global_load_dword v64, v[64:65], off nt
	s_nop 0
	global_load_dword v65, v[66:67], off nt
	v_lshl_add_u64 v[66:67], v[2:3], 0, s[4:5]
	s_lshl_b32 s4, s1, 8
	s_min_u32 s1, s0, 64
	v_lshl_add_u64 v[68:69], v[2:3], 0, s[4:5]
	s_lshl_b32 s4, s1, 8
	s_min_u32 s1, s0, 0x41
	global_load_dword v66, v[66:67], off nt
	s_nop 0
	global_load_dword v67, v[68:69], off nt
	v_lshl_add_u64 v[68:69], v[2:3], 0, s[4:5]
	s_lshl_b32 s4, s1, 8
	s_min_u32 s1, s0, 0x42
	global_load_dword v115, v[68:69], off nt
	v_lshl_add_u64 v[68:69], v[2:3], 0, s[4:5]
	s_lshl_b32 s4, s1, 8
	s_min_u32 s1, s0, 0x43
	global_load_dword v116, v[68:69], off nt
	v_lshl_add_u64 v[68:69], v[2:3], 0, s[4:5]
	s_lshl_b32 s4, s1, 8
	s_min_u32 s1, s0, 0x44
	global_load_dword v117, v[68:69], off nt
	v_lshl_add_u64 v[68:69], v[2:3], 0, s[4:5]
	s_lshl_b32 s4, s1, 8
	s_min_u32 s1, s0, 0x45
	global_load_dword v118, v[68:69], off nt
	v_lshl_add_u64 v[68:69], v[2:3], 0, s[4:5]
	s_lshl_b32 s4, s1, 8
	s_min_u32 s1, s0, 0x46
	global_load_dword v119, v[68:69], off nt
	v_lshl_add_u64 v[68:69], v[2:3], 0, s[4:5]
	s_lshl_b32 s4, s1, 8
	s_min_u32 s1, s0, 0x47
	global_load_dword v120, v[68:69], off nt
	v_lshl_add_u64 v[68:69], v[2:3], 0, s[4:5]
	s_lshl_b32 s4, s1, 8
	s_min_u32 s1, s0, 0x48
	global_load_dword v121, v[68:69], off nt
	v_lshl_add_u64 v[68:69], v[2:3], 0, s[4:5]
	s_lshl_b32 s4, s1, 8
	s_min_u32 s1, s0, 0x49
	global_load_dword v123, v[68:69], off nt
	v_lshl_add_u64 v[68:69], v[2:3], 0, s[4:5]
	s_lshl_b32 s4, s1, 8
	s_min_u32 s1, s0, 0x4a
	global_load_dword v122, v[68:69], off nt
	v_lshl_add_u64 v[68:69], v[2:3], 0, s[4:5]
	s_lshl_b32 s4, s1, 8
	s_min_u32 s1, s0, 0x4b
	global_load_dword v140, v[68:69], off nt
	v_lshl_add_u64 v[68:69], v[2:3], 0, s[4:5]
	s_lshl_b32 s4, s1, 8
	s_min_u32 s1, s0, 0x4c
	global_load_dword v141, v[68:69], off nt
	v_lshl_add_u64 v[68:69], v[2:3], 0, s[4:5]
	s_lshl_b32 s4, s1, 8
	s_min_u32 s1, s0, 0x4d
	global_load_dword v142, v[68:69], off nt
	v_lshl_add_u64 v[68:69], v[2:3], 0, s[4:5]
	s_lshl_b32 s4, s1, 8
	s_min_u32 s1, s0, 0x4e
	global_load_dword v143, v[68:69], off nt
	v_lshl_add_u64 v[68:69], v[2:3], 0, s[4:5]
	s_lshl_b32 s4, s1, 8
	s_min_u32 s1, s0, 0x4f
	global_load_dword v144, v[68:69], off nt
	v_lshl_add_u64 v[68:69], v[2:3], 0, s[4:5]
	s_lshl_b32 s4, s1, 8
	s_min_u32 s1, s0, 0x50
	global_load_dword v145, v[68:69], off nt
	v_lshl_add_u64 v[68:69], v[2:3], 0, s[4:5]
	s_lshl_b32 s4, s1, 8
	s_min_u32 s1, s0, 0x51
	global_load_dword v147, v[68:69], off nt
	v_lshl_add_u64 v[68:69], v[2:3], 0, s[4:5]
	s_lshl_b32 s4, s1, 8
	s_min_u32 s1, s0, 0x52
	global_load_dword v146, v[68:69], off nt
	v_lshl_add_u64 v[68:69], v[2:3], 0, s[4:5]
	s_lshl_b32 s4, s1, 8
	s_min_u32 s1, s0, 0x53
	global_load_dword v148, v[68:69], off nt
	v_lshl_add_u64 v[68:69], v[2:3], 0, s[4:5]
	s_lshl_b32 s4, s1, 8
	s_min_u32 s1, s0, 0x54
	global_load_dword v149, v[68:69], off nt
	v_lshl_add_u64 v[68:69], v[2:3], 0, s[4:5]
; __device__ __forceinline__ void topk_row(const Params& p, int r, int lane, __attribute__((address_space(3))) int* out) {
;     ...
; #pragma unroll
;     for (int i = 0; i < 128; ++i) {
;       const int ic = min(i, nch - 1);
;       key[i] = __float_as_uint(scl[ic * 64]);
;     }
	s_lshl_b32 s4, s1, 8
	s_min_u32 s1, s0, 0x55
	global_load_dword v150, v[68:69], off nt
	v_lshl_add_u64 v[68:69], v[2:3], 0, s[4:5]
	s_lshl_b32 s4, s1, 8
	s_min_u32 s1, s0, 0x56
	global_load_dword v151, v[68:69], off nt
	v_lshl_add_u64 v[68:69], v[2:3], 0, s[4:5]
	s_lshl_b32 s4, s1, 8
	s_min_u32 s1, s0, 0x57
	global_load_dword v152, v[68:69], off nt
	v_lshl_add_u64 v[68:69], v[2:3], 0, s[4:5]
	s_lshl_b32 s4, s1, 8
	s_min_u32 s1, s0, 0x58
	global_load_dword v153, v[68:69], off nt
	v_lshl_add_u64 v[68:69], v[2:3], 0, s[4:5]
	s_lshl_b32 s4, s1, 8
	s_min_u32 s1, s0, 0x59
	global_load_dword v155, v[68:69], off nt
	v_lshl_add_u64 v[68:69], v[2:3], 0, s[4:5]
	s_lshl_b32 s4, s1, 8
	s_min_u32 s1, s0, 0x5a
	global_load_dword v154, v[68:69], off nt
	v_lshl_add_u64 v[68:69], v[2:3], 0, s[4:5]
	s_lshl_b32 s4, s1, 8
	s_min_u32 s1, s0, 0x5b
	global_load_dword v156, v[68:69], off nt
	v_lshl_add_u64 v[68:69], v[2:3], 0, s[4:5]
	s_lshl_b32 s4, s1, 8
	s_min_u32 s1, s0, 0x5c
	global_load_dword v157, v[68:69], off nt
	v_lshl_add_u64 v[68:69], v[2:3], 0, s[4:5]
	s_lshl_b32 s4, s1, 8
	s_min_u32 s1, s0, 0x5d
	global_load_dword v158, v[68:69], off nt
	v_lshl_add_u64 v[68:69], v[2:3], 0, s[4:5]
	s_lshl_b32 s4, s1, 8
	s_min_u32 s1, s0, 0x5e
	global_load_dword v159, v[68:69], off nt
	v_lshl_add_u64 v[68:69], v[2:3], 0, s[4:5]
	s_lshl_b32 s4, s1, 8
	s_min_u32 s1, s0, 0x5f
	global_load_dword v160, v[68:69], off nt
	v_lshl_add_u64 v[68:69], v[2:3], 0, s[4:5]
	s_lshl_b32 s4, s1, 8
	s_min_u32 s1, s0, 0x60
	global_load_dword v161, v[68:69], off nt
	v_lshl_add_u64 v[68:69], v[2:3], 0, s[4:5]
	s_lshl_b32 s4, s1, 8
	s_min_u32 s1, s0, 0x61
	global_load_dword v163, v[68:69], off nt
	v_lshl_add_u64 v[68:69], v[2:3], 0, s[4:5]
	s_lshl_b32 s4, s1, 8
	s_min_u32 s1, s0, 0x62
	global_load_dword v162, v[68:69], off nt
	v_lshl_add_u64 v[68:69], v[2:3], 0, s[4:5]
	s_lshl_b32 s4, s1, 8
	s_min_u32 s1, s0, 0x63
	global_load_dword v164, v[68:69], off nt
	v_lshl_add_u64 v[68:69], v[2:3], 0, s[4:5]
	s_lshl_b32 s4, s1, 8
	s_min_u32 s1, s0, 0x64
	global_load_dword v165, v[68:69], off nt
	v_lshl_add_u64 v[68:69], v[2:3], 0, s[4:5]
	s_lshl_b32 s4, s1, 8
	s_min_u32 s1, s0, 0x65
	global_load_dword v166, v[68:69], off nt
	v_lshl_add_u64 v[68:69], v[2:3], 0, s[4:5]
	s_lshl_b32 s4, s1, 8
	s_min_u32 s1, s0, 0x66
	global_load_dword v167, v[68:69], off nt
	v_lshl_add_u64 v[68:69], v[2:3], 0, s[4:5]
	s_lshl_b32 s4, s1, 8
	s_min_u32 s1, s0, 0x67
	global_load_dword v168, v[68:69], off nt
	v_lshl_add_u64 v[68:69], v[2:3], 0, s[4:5]
	s_lshl_b32 s4, s1, 8
	s_min_u32 s1, s0, 0x68
	global_load_dword v169, v[68:69], off nt
	v_lshl_add_u64 v[68:69], v[2:3], 0, s[4:5]
	s_lshl_b32 s4, s1, 8
	s_min_u32 s1, s0, 0x69
	global_load_dword v171, v[68:69], off nt
	v_lshl_add_u64 v[68:69], v[2:3], 0, s[4:5]
	s_lshl_b32 s4, s1, 8
	s_min_u32 s1, s0, 0x6a
	global_load_dword v170, v[68:69], off nt
	v_lshl_add_u64 v[68:69], v[2:3], 0, s[4:5]
	s_lshl_b32 s4, s1, 8
	s_min_u32 s1, s0, 0x6b
	global_load_dword v172, v[68:69], off nt
	v_lshl_add_u64 v[68:69], v[2:3], 0, s[4:5]
	s_lshl_b32 s4, s1, 8
	s_min_u32 s1, s0, 0x6c
	global_load_dword v173, v[68:69], off nt
	v_lshl_add_u64 v[68:69], v[2:3], 0, s[4:5]
	s_lshl_b32 s4, s1, 8
	s_min_u32 s1, s0, 0x6d
	global_load_dword v174, v[68:69], off nt
	v_lshl_add_u64 v[68:69], v[2:3], 0, s[4:5]
	s_lshl_b32 s4, s1, 8
	s_min_u32 s1, s0, 0x6e
	global_load_dword v175, v[68:69], off nt
	v_lshl_add_u64 v[68:69], v[2:3], 0, s[4:5]
	s_lshl_b32 s4, s1, 8
	s_min_u32 s1, s0, 0x6f
	global_load_dword v176, v[68:69], off nt
	v_lshl_add_u64 v[68:69], v[2:3], 0, s[4:5]
	s_lshl_b32 s4, s1, 8
	s_min_u32 s1, s0, 0x70
	global_load_dword v177, v[68:69], off nt
	v_lshl_add_u64 v[68:69], v[2:3], 0, s[4:5]
	s_lshl_b32 s4, s1, 8
	s_min_u32 s1, s0, 0x71
	global_load_dword v179, v[68:69], off nt
	v_lshl_add_u64 v[68:69], v[2:3], 0, s[4:5]
	s_lshl_b32 s4, s1, 8
	s_min_u32 s1, s0, 0x72
	global_load_dword v178, v[68:69], off nt
	v_lshl_add_u64 v[68:69], v[2:3], 0, s[4:5]
	s_lshl_b32 s4, s1, 8
	s_min_u32 s1, s0, 0x73
	global_load_dword v180, v[68:69], off nt
	v_lshl_add_u64 v[68:69], v[2:3], 0, s[4:5]
	s_lshl_b32 s4, s1, 8
	s_min_u32 s1, s0, 0x74
	global_load_dword v181, v[68:69], off nt
	v_lshl_add_u64 v[68:69], v[2:3], 0, s[4:5]
	s_lshl_b32 s4, s1, 8
	s_min_u32 s1, s0, 0x75
	global_load_dword v182, v[68:69], off nt
	v_lshl_add_u64 v[68:69], v[2:3], 0, s[4:5]
	s_lshl_b32 s4, s1, 8
	s_min_u32 s1, s0, 0x76
	global_load_dword v183, v[68:69], off nt
	v_lshl_add_u64 v[68:69], v[2:3], 0, s[4:5]
	s_lshl_b32 s4, s1, 8
	s_min_u32 s1, s0, 0x77
	global_load_dword v184, v[68:69], off nt
	v_lshl_add_u64 v[68:69], v[2:3], 0, s[4:5]
	s_lshl_b32 s4, s1, 8
	s_min_u32 s1, s0, 0x78
	global_load_dword v185, v[68:69], off nt
	v_lshl_add_u64 v[68:69], v[2:3], 0, s[4:5]
	s_lshl_b32 s4, s1, 8
	s_min_u32 s1, s0, 0x79
	global_load_dword v187, v[68:69], off nt
	v_lshl_add_u64 v[68:69], v[2:3], 0, s[4:5]
	s_lshl_b32 s4, s1, 8
	s_min_u32 s1, s0, 0x7a
	global_load_dword v186, v[68:69], off nt
	v_lshl_add_u64 v[68:69], v[2:3], 0, s[4:5]
	s_lshl_b32 s4, s1, 8
	s_min_u32 s1, s0, 0x7b
	global_load_dword v188, v[68:69], off nt
	v_lshl_add_u64 v[68:69], v[2:3], 0, s[4:5]
	s_lshl_b32 s4, s1, 8
	s_min_u32 s1, s0, 0x7c
	global_load_dword v189, v[68:69], off nt
	v_lshl_add_u64 v[68:69], v[2:3], 0, s[4:5]
	s_lshl_b32 s4, s1, 8
	s_min_u32 s1, s0, 0x7d
	global_load_dword v190, v[68:69], off nt
	v_lshl_add_u64 v[68:69], v[2:3], 0, s[4:5]
	s_lshl_b32 s4, s1, 8
	s_min_u32 s1, s0, 0x7e
	global_load_dword v191, v[68:69], off nt
	v_lshl_add_u64 v[68:69], v[2:3], 0, s[4:5]
	s_lshl_b32 s4, s1, 8
	global_load_dword v192, v[68:69], off nt
	v_lshl_add_u64 v[68:69], v[2:3], 0, s[4:5]
	s_lshl_b32 s4, s0, 6
	v_lshl_add_u64 v[2:3], s[4:5], 2, v[2:3]
	global_load_dword v193, v[68:69], off nt
	global_load_dword v194, v[2:3], off nt
	s_waitcnt vmcnt(0)
; __device__ __forceinline__ void topk_row(const Params& p, int r, int lane, __attribute__((address_space(3))) int* out) {
;     ...
; #pragma unroll
;     for (int i = 0; i < 128; ++i) {
;       const int lim = n - i * 64;
;       const unsigned u = key[i];
;       key[i] = (lo < lim) ? ((u >> 31) ? ~u : (u | 0x80000000u)) : 0u;
;     }
;     __builtin_amdgcn_sched_barrier(0);
	v_not_b32_e32 v2, v9
	v_cmp_gt_i32_e32 vcc, 0, v9
	s_sub_i32 s0, s15, 63
	s_nop 0
	v_cndmask_b32_e64 v2, -|v9|, v2, vcc
	v_cmp_ge_i32_e32 vcc, s15, v0
	s_nop 1
	v_cndmask_b32_e32 v139, 0, v2, vcc
	v_not_b32_e32 v2, v8
	v_cmp_gt_i32_e32 vcc, 0, v8
	s_nop 1
	v_cndmask_b32_e64 v2, -|v8|, v2, vcc
	v_cmp_gt_i32_e32 vcc, s0, v0
	s_add_i32 s0, s15, 0xffffff81
	s_nop 0
	v_cndmask_b32_e32 v138, 0, v2, vcc
	v_not_b32_e32 v2, v7
	v_cmp_gt_i32_e32 vcc, 0, v7
	s_nop 1
	v_cndmask_b32_e64 v2, -|v7|, v2, vcc
	v_cmp_gt_i32_e32 vcc, s0, v0
	s_add_i32 s0, s15, 0xffffff41
	s_nop 0
	v_cndmask_b32_e32 v137, 0, v2, vcc
	v_not_b32_e32 v2, v4
	v_cmp_gt_i32_e32 vcc, 0, v4
	s_nop 1
	v_cndmask_b32_e64 v2, -|v4|, v2, vcc
	v_cmp_gt_i32_e32 vcc, s0, v0
	s_add_i32 s0, s15, 0xffffff01
	s_nop 0
	v_cndmask_b32_e32 v136, 0, v2, vcc
	v_not_b32_e32 v2, v1
	v_cmp_gt_i32_e32 vcc, 0, v1
	s_nop 1
	v_cndmask_b32_e64 v1, -|v1|, v2, vcc
	v_cmp_gt_i32_e32 vcc, s0, v0
	s_add_i32 s0, s15, 0xfffffec1
	s_nop 0
	v_cndmask_b32_e32 v135, 0, v1, vcc
	v_not_b32_e32 v1, v5
	v_cmp_gt_i32_e32 vcc, 0, v5
	s_nop 1
	v_cndmask_b32_e64 v1, -|v5|, v1, vcc
	v_cmp_gt_i32_e32 vcc, s0, v0
	s_add_i32 s0, s15, 0xfffffe81
	s_nop 0
	v_cndmask_b32_e32 v134, 0, v1, vcc
	v_not_b32_e32 v1, v6
	v_cmp_gt_i32_e32 vcc, 0, v6
	s_nop 1
	v_cndmask_b32_e64 v1, -|v6|, v1, vcc
	v_cmp_gt_i32_e32 vcc, s0, v0
	s_add_i32 s0, s15, 0xfffffe41
	s_nop 0
	v_cndmask_b32_e32 v133, 0, v1, vcc
	v_not_b32_e32 v1, v11
	v_cmp_gt_i32_e32 vcc, 0, v11
	s_nop 1
	v_cndmask_b32_e64 v1, -|v11|, v1, vcc
	v_cmp_gt_i32_e32 vcc, s0, v0
	s_add_i32 s0, s15, 0xfffffe01
	s_nop 0
	v_cndmask_b32_e32 v132, 0, v1, vcc
	v_not_b32_e32 v1, v10
	v_cmp_gt_i32_e32 vcc, 0, v10
	s_nop 1
	v_cndmask_b32_e64 v1, -|v10|, v1, vcc
	v_cmp_gt_i32_e32 vcc, s0, v0
	s_add_i32 s0, s15, 0xfffffdc1
	s_nop 0
	v_cndmask_b32_e32 v131, 0, v1, vcc
	v_not_b32_e32 v1, v12
	v_cmp_gt_i32_e32 vcc, 0, v12
	s_nop 1
	v_cndmask_b32_e64 v1, -|v12|, v1, vcc
	v_cmp_gt_i32_e32 vcc, s0, v0
	s_add_i32 s0, s15, 0xfffffd81
	s_nop 0
	v_cndmask_b32_e32 v130, 0, v1, vcc
	v_not_b32_e32 v1, v13
	v_cmp_gt_i32_e32 vcc, 0, v13
	s_nop 1
	v_cndmask_b32_e64 v1, -|v13|, v1, vcc
	v_cmp_gt_i32_e32 vcc, s0, v0
	s_add_i32 s0, s15, 0xfffffd41
	s_nop 0
	v_cndmask_b32_e32 v129, 0, v1, vcc
	v_not_b32_e32 v1, v14
	v_cmp_gt_i32_e32 vcc, 0, v14
	s_nop 1
	v_cndmask_b32_e64 v1, -|v14|, v1, vcc
	v_cmp_gt_i32_e32 vcc, s0, v0
	s_add_i32 s0, s15, 0xfffffd01
	s_nop 0
	v_cndmask_b32_e32 v128, 0, v1, vcc
	v_not_b32_e32 v1, v15
	v_cmp_gt_i32_e32 vcc, 0, v15
	s_nop 1
	v_cndmask_b32_e64 v1, -|v15|, v1, vcc
	v_cmp_gt_i32_e32 vcc, s0, v0
	s_add_i32 s0, s15, 0xfffffcc1
	s_nop 0
	v_cndmask_b32_e32 v127, 0, v1, vcc
	v_not_b32_e32 v1, v16
	v_cmp_gt_i32_e32 vcc, 0, v16
	s_nop 1
	v_cndmask_b32_e64 v1, -|v16|, v1, vcc
	v_cmp_gt_i32_e32 vcc, s0, v0
	s_add_i32 s0, s15, 0xfffffc81
	s_nop 0
	v_cndmask_b32_e32 v126, 0, v1, vcc
	v_not_b32_e32 v1, v17
	v_cmp_gt_i32_e32 vcc, 0, v17
	s_nop 1
	v_cndmask_b32_e64 v1, -|v17|, v1, vcc
	v_cmp_gt_i32_e32 vcc, s0, v0
	s_add_i32 s0, s15, 0xfffffc41
	s_nop 0
	v_cndmask_b32_e32 v125, 0, v1, vcc
	v_not_b32_e32 v1, v19
	v_cmp_gt_i32_e32 vcc, 0, v19
	s_nop 1
	v_cndmask_b32_e64 v1, -|v19|, v1, vcc
	v_cmp_gt_i32_e32 vcc, s0, v0
	s_add_i32 s0, s15, 0xfffffc01
	s_nop 0
	v_cndmask_b32_e32 v124, 0, v1, vcc
	v_not_b32_e32 v1, v18
	v_cmp_gt_i32_e32 vcc, 0, v18
	s_nop 1
	v_cndmask_b32_e64 v1, -|v18|, v1, vcc
	v_cmp_gt_i32_e32 vcc, s0, v0
	s_add_i32 s0, s15, 0xfffffbc1
	s_nop 0
	v_cndmask_b32_e32 v114, 0, v1, vcc
	v_not_b32_e32 v1, v20
	v_cmp_gt_i32_e32 vcc, 0, v20
	s_nop 1
	v_cndmask_b32_e64 v1, -|v20|, v1, vcc
	v_cmp_gt_i32_e32 vcc, s0, v0
	s_add_i32 s0, s15, 0xfffffb81
	s_nop 0
	v_cndmask_b32_e32 v113, 0, v1, vcc
	v_not_b32_e32 v1, v21
	v_cmp_gt_i32_e32 vcc, 0, v21
	s_nop 1
	v_cndmask_b32_e64 v1, -|v21|, v1, vcc
	v_cmp_gt_i32_e32 vcc, s0, v0
	s_add_i32 s0, s15, 0xfffffb41
	s_nop 0
	v_cndmask_b32_e32 v112, 0, v1, vcc
	v_not_b32_e32 v1, v22
	v_cmp_gt_i32_e32 vcc, 0, v22
	s_nop 1
	v_cndmask_b32_e64 v1, -|v22|, v1, vcc
	v_cmp_gt_i32_e32 vcc, s0, v0
	s_add_i32 s0, s15, 0xfffffb01
	s_nop 0
	v_cndmask_b32_e32 v111, 0, v1, vcc
	v_not_b32_e32 v1, v23
	v_cmp_gt_i32_e32 vcc, 0, v23
	s_nop 1
	v_cndmask_b32_e64 v1, -|v23|, v1, vcc
	v_cmp_gt_i32_e32 vcc, s0, v0
	s_add_i32 s0, s15, 0xfffffac1
	s_nop 0
	v_cndmask_b32_e32 v110, 0, v1, vcc
	v_not_b32_e32 v1, v24
	v_cmp_gt_i32_e32 vcc, 0, v24
	s_nop 1
	v_cndmask_b32_e64 v1, -|v24|, v1, vcc
	v_cmp_gt_i32_e32 vcc, s0, v0
	s_add_i32 s0, s15, 0xfffffa81
	s_nop 0
	v_cndmask_b32_e32 v109, 0, v1, vcc
	v_not_b32_e32 v1, v25
	v_cmp_gt_i32_e32 vcc, 0, v25
	s_nop 1
	v_cndmask_b32_e64 v1, -|v25|, v1, vcc
	v_cmp_gt_i32_e32 vcc, s0, v0
	s_add_i32 s0, s15, 0xfffffa41
	s_nop 0
	v_cndmask_b32_e32 v108, 0, v1, vcc
	v_not_b32_e32 v1, v27
	v_cmp_gt_i32_e32 vcc, 0, v27
	s_nop 1
	v_cndmask_b32_e64 v1, -|v27|, v1, vcc
	v_cmp_gt_i32_e32 vcc, s0, v0
	s_add_i32 s0, s15, 0xfffffa01
	s_nop 0
	v_cndmask_b32_e32 v107, 0, v1, vcc
	v_not_b32_e32 v1, v26
	v_cmp_gt_i32_e32 vcc, 0, v26
	s_nop 1
	v_cndmask_b32_e64 v1, -|v26|, v1, vcc
	v_cmp_gt_i32_e32 vcc, s0, v0
	s_add_i32 s0, s15, 0xfffff9c1
	s_nop 0
	v_cndmask_b32_e32 v106, 0, v1, vcc
	v_not_b32_e32 v1, v28
	v_cmp_gt_i32_e32 vcc, 0, v28
	s_nop 1
	v_cndmask_b32_e64 v1, -|v28|, v1, vcc
	v_cmp_gt_i32_e32 vcc, s0, v0
	s_add_i32 s0, s15, 0xfffff981
	s_nop 0
	v_cndmask_b32_e32 v105, 0, v1, vcc
	v_not_b32_e32 v1, v29
	v_cmp_gt_i32_e32 vcc, 0, v29
	s_nop 1
	v_cndmask_b32_e64 v1, -|v29|, v1, vcc
	v_cmp_gt_i32_e32 vcc, s0, v0
	s_add_i32 s0, s15, 0xfffff941
	s_nop 0
	v_cndmask_b32_e32 v104, 0, v1, vcc
	v_not_b32_e32 v1, v30
	v_cmp_gt_i32_e32 vcc, 0, v30
	s_nop 1
; __device__ __forceinline__ void topk_row(const Params& p, int r, int lane, __attribute__((address_space(3))) int* out) {
;     ...
; #pragma unroll
;     for (int i = 0; i < 128; ++i) {
;       const int lim = n - i * 64;
;       const unsigned u = key[i];
;       key[i] = (lo < lim) ? ((u >> 31) ? ~u : (u | 0x80000000u)) : 0u;
;     }
;     __builtin_amdgcn_sched_barrier(0);
	v_cndmask_b32_e64 v1, -|v30|, v1, vcc
	v_cmp_gt_i32_e32 vcc, s0, v0
	s_add_i32 s0, s15, 0xfffff901
	s_nop 0
	v_cndmask_b32_e32 v103, 0, v1, vcc
	v_not_b32_e32 v1, v31
	v_cmp_gt_i32_e32 vcc, 0, v31
	s_nop 1
	v_cndmask_b32_e64 v1, -|v31|, v1, vcc
	v_cmp_gt_i32_e32 vcc, s0, v0
	s_add_i32 s0, s15, 0xfffff8c1
	s_nop 0
	v_cndmask_b32_e32 v102, 0, v1, vcc
	v_not_b32_e32 v1, v32
	v_cmp_gt_i32_e32 vcc, 0, v32
	s_nop 1
	v_cndmask_b32_e64 v1, -|v32|, v1, vcc
	v_cmp_gt_i32_e32 vcc, s0, v0
	s_add_i32 s0, s15, 0xfffff881
	s_nop 0
	v_cndmask_b32_e32 v101, 0, v1, vcc
	v_not_b32_e32 v1, v34
	v_cmp_gt_i32_e32 vcc, 0, v34
	s_nop 1
	v_cndmask_b32_e64 v1, -|v34|, v1, vcc
	v_cmp_gt_i32_e32 vcc, s0, v0
	s_add_i32 s0, s15, 0xfffff841
	s_nop 0
	v_cndmask_b32_e32 v100, 0, v1, vcc
	v_not_b32_e32 v1, v36
	v_cmp_gt_i32_e32 vcc, 0, v36
	s_nop 1
	v_cndmask_b32_e64 v1, -|v36|, v1, vcc
	v_cmp_gt_i32_e32 vcc, s0, v0
	s_add_i32 s0, s15, 0xfffff801
	s_nop 0
	v_cndmask_b32_e32 v99, 0, v1, vcc
	v_not_b32_e32 v1, v35
	v_cmp_gt_i32_e32 vcc, 0, v35
	s_nop 1
	v_cndmask_b32_e64 v1, -|v35|, v1, vcc
	v_cmp_gt_i32_e32 vcc, s0, v0
	s_add_i32 s0, s15, 0xfffff7c1
	s_nop 0
	v_cndmask_b32_e32 v98, 0, v1, vcc
	v_not_b32_e32 v1, v37
	v_cmp_gt_i32_e32 vcc, 0, v37
	s_nop 1
	v_cndmask_b32_e64 v1, -|v37|, v1, vcc
	v_cmp_gt_i32_e32 vcc, s0, v0
	s_add_i32 s0, s15, 0xfffff781
	s_nop 0
	v_cndmask_b32_e32 v97, 0, v1, vcc
	v_not_b32_e32 v1, v38
	v_cmp_gt_i32_e32 vcc, 0, v38
	s_nop 1
	v_cndmask_b32_e64 v1, -|v38|, v1, vcc
	v_cmp_gt_i32_e32 vcc, s0, v0
	s_add_i32 s0, s15, 0xfffff741
	s_nop 0
	v_cndmask_b32_e32 v96, 0, v1, vcc
	v_not_b32_e32 v1, v39
	v_cmp_gt_i32_e32 vcc, 0, v39
	s_nop 1
	v_cndmask_b32_e64 v1, -|v39|, v1, vcc
	v_cmp_gt_i32_e32 vcc, s0, v0
	s_add_i32 s0, s15, 0xfffff701
	s_nop 0
	v_cndmask_b32_e32 v95, 0, v1, vcc
	v_not_b32_e32 v1, v40
	v_cmp_gt_i32_e32 vcc, 0, v40
	s_nop 1
	v_cndmask_b32_e64 v1, -|v40|, v1, vcc
	v_cmp_gt_i32_e32 vcc, s0, v0
	s_add_i32 s0, s15, 0xfffff6c1
	s_nop 0
	v_cndmask_b32_e32 v94, 0, v1, vcc
	v_not_b32_e32 v1, v41
	v_cmp_gt_i32_e32 vcc, 0, v41
	s_nop 1
	v_cndmask_b32_e64 v1, -|v41|, v1, vcc
	v_cmp_gt_i32_e32 vcc, s0, v0
	s_add_i32 s0, s15, 0xfffff681
	s_nop 0
	v_cndmask_b32_e32 v93, 0, v1, vcc
	v_not_b32_e32 v1, v42
	v_cmp_gt_i32_e32 vcc, 0, v42
	s_nop 1
	v_cndmask_b32_e64 v1, -|v42|, v1, vcc
	v_cmp_gt_i32_e32 vcc, s0, v0
	s_add_i32 s0, s15, 0xfffff641
	s_nop 0
	v_cndmask_b32_e32 v92, 0, v1, vcc
	v_not_b32_e32 v1, v44
	v_cmp_gt_i32_e32 vcc, 0, v44
	s_nop 1
	v_cndmask_b32_e64 v1, -|v44|, v1, vcc
	v_cmp_gt_i32_e32 vcc, s0, v0
	s_add_i32 s0, s15, 0xfffff601
	s_nop 0
	v_cndmask_b32_e32 v91, 0, v1, vcc
	v_not_b32_e32 v1, v43
	v_cmp_gt_i32_e32 vcc, 0, v43
	s_nop 1
	v_cndmask_b32_e64 v1, -|v43|, v1, vcc
	v_cmp_gt_i32_e32 vcc, s0, v0
	s_add_i32 s0, s15, 0xfffff5c1
	s_nop 0
	v_cndmask_b32_e32 v90, 0, v1, vcc
	v_not_b32_e32 v1, v45
	v_cmp_gt_i32_e32 vcc, 0, v45
	s_nop 1
	v_cndmask_b32_e64 v1, -|v45|, v1, vcc
	v_cmp_gt_i32_e32 vcc, s0, v0
	s_add_i32 s0, s15, 0xfffff581
	s_nop 0
	v_cndmask_b32_e32 v89, 0, v1, vcc
	v_not_b32_e32 v1, v46
	v_cmp_gt_i32_e32 vcc, 0, v46
	s_nop 1
	v_cndmask_b32_e64 v1, -|v46|, v1, vcc
	v_cmp_gt_i32_e32 vcc, s0, v0
	s_add_i32 s0, s15, 0xfffff541
	s_nop 0
	v_cndmask_b32_e32 v88, 0, v1, vcc
	v_not_b32_e32 v1, v47
	v_cmp_gt_i32_e32 vcc, 0, v47
	s_nop 1
	v_cndmask_b32_e64 v1, -|v47|, v1, vcc
	v_cmp_gt_i32_e32 vcc, s0, v0
	s_add_i32 s0, s15, 0xfffff501
	s_nop 0
	v_cndmask_b32_e32 v87, 0, v1, vcc
	v_not_b32_e32 v1, v48
	v_cmp_gt_i32_e32 vcc, 0, v48
	s_nop 1
	v_cndmask_b32_e64 v1, -|v48|, v1, vcc
	v_cmp_gt_i32_e32 vcc, s0, v0
	s_add_i32 s0, s15, 0xfffff4c1
	s_nop 0
	v_cndmask_b32_e32 v86, 0, v1, vcc
	v_not_b32_e32 v1, v49
	v_cmp_gt_i32_e32 vcc, 0, v49
	s_nop 1
	v_cndmask_b32_e64 v1, -|v49|, v1, vcc
	v_cmp_gt_i32_e32 vcc, s0, v0
	s_add_i32 s0, s15, 0xfffff481
	s_nop 0
	v_cndmask_b32_e32 v85, 0, v1, vcc
	v_not_b32_e32 v1, v50
	v_cmp_gt_i32_e32 vcc, 0, v50
	s_nop 1
	v_cndmask_b32_e64 v1, -|v50|, v1, vcc
	v_cmp_gt_i32_e32 vcc, s0, v0
	s_add_i32 s0, s15, 0xfffff441
	s_nop 0
	v_cndmask_b32_e32 v84, 0, v1, vcc
	v_not_b32_e32 v1, v52
	v_cmp_gt_i32_e32 vcc, 0, v52
	s_nop 1
	v_cndmask_b32_e64 v1, -|v52|, v1, vcc
	v_cmp_gt_i32_e32 vcc, s0, v0
	s_add_i32 s0, s15, 0xfffff401
	s_nop 0
	v_cndmask_b32_e32 v83, 0, v1, vcc
	v_not_b32_e32 v1, v51
	v_cmp_gt_i32_e32 vcc, 0, v51
	s_nop 1
	v_cndmask_b32_e64 v1, -|v51|, v1, vcc
	v_cmp_gt_i32_e32 vcc, s0, v0
	s_add_i32 s0, s15, 0xfffff3c1
	s_nop 0
	v_cndmask_b32_e32 v82, 0, v1, vcc
	v_not_b32_e32 v1, v53
	v_cmp_gt_i32_e32 vcc, 0, v53
	s_nop 1
	v_cndmask_b32_e64 v1, -|v53|, v1, vcc
	v_cmp_gt_i32_e32 vcc, s0, v0
	s_add_i32 s0, s15, 0xfffff381
	s_nop 0
	v_cndmask_b32_e32 v81, 0, v1, vcc
	v_not_b32_e32 v1, v54
	v_cmp_gt_i32_e32 vcc, 0, v54
	s_nop 1
	v_cndmask_b32_e64 v1, -|v54|, v1, vcc
	v_cmp_gt_i32_e32 vcc, s0, v0
	s_add_i32 s0, s15, 0xfffff341
	s_nop 0
	v_cndmask_b32_e32 v80, 0, v1, vcc
	v_not_b32_e32 v1, v55
	v_cmp_gt_i32_e32 vcc, 0, v55
	s_nop 1
	v_cndmask_b32_e64 v1, -|v55|, v1, vcc
	v_cmp_gt_i32_e32 vcc, s0, v0
	s_add_i32 s0, s15, 0xfffff301
	s_nop 0
	v_cndmask_b32_e32 v79, 0, v1, vcc
	v_not_b32_e32 v1, v56
	v_cmp_gt_i32_e32 vcc, 0, v56
	s_nop 1
	v_cndmask_b32_e64 v1, -|v56|, v1, vcc
	v_cmp_gt_i32_e32 vcc, s0, v0
	s_add_i32 s0, s15, 0xfffff2c1
	s_nop 0
	v_cndmask_b32_e32 v78, 0, v1, vcc
	v_not_b32_e32 v1, v57
	v_cmp_gt_i32_e32 vcc, 0, v57
	s_nop 1
	v_cndmask_b32_e64 v1, -|v57|, v1, vcc
	v_cmp_gt_i32_e32 vcc, s0, v0
	s_add_i32 s0, s15, 0xfffff281
	s_nop 0
	v_cndmask_b32_e32 v77, 0, v1, vcc
	v_not_b32_e32 v1, v58
	v_cmp_gt_i32_e32 vcc, 0, v58
	s_nop 1
	v_cndmask_b32_e64 v1, -|v58|, v1, vcc
	v_cmp_gt_i32_e32 vcc, s0, v0
; __device__ __forceinline__ void topk_row(const Params& p, int r, int lane, __attribute__((address_space(3))) int* out) {
;     ...
; #pragma unroll
;     for (int i = 0; i < 128; ++i) {
;       const int lim = n - i * 64;
;       const unsigned u = key[i];
;       key[i] = (lo < lim) ? ((u >> 31) ? ~u : (u | 0x80000000u)) : 0u;
;     }
;     __builtin_amdgcn_sched_barrier(0);
	s_add_i32 s0, s15, 0xfffff241
	s_nop 0
	v_cndmask_b32_e32 v76, 0, v1, vcc
	v_not_b32_e32 v1, v60
	v_cmp_gt_i32_e32 vcc, 0, v60
	s_nop 1
	v_cndmask_b32_e64 v1, -|v60|, v1, vcc
	v_cmp_gt_i32_e32 vcc, s0, v0
	s_add_i32 s0, s15, 0xfffff201
	s_nop 0
	v_cndmask_b32_e32 v75, 0, v1, vcc
	v_not_b32_e32 v1, v59
	v_cmp_gt_i32_e32 vcc, 0, v59
	s_nop 1
	v_cndmask_b32_e64 v1, -|v59|, v1, vcc
	v_cmp_gt_i32_e32 vcc, s0, v0
	s_add_i32 s0, s15, 0xfffff1c1
	s_nop 0
	v_cndmask_b32_e32 v74, 0, v1, vcc
	v_not_b32_e32 v1, v61
	v_cmp_gt_i32_e32 vcc, 0, v61
	s_nop 1
	v_cndmask_b32_e64 v1, -|v61|, v1, vcc
	v_cmp_gt_i32_e32 vcc, s0, v0
	s_add_i32 s0, s15, 0xfffff181
	s_nop 0
	v_cndmask_b32_e32 v73, 0, v1, vcc
	v_not_b32_e32 v1, v62
	v_cmp_gt_i32_e32 vcc, 0, v62
	s_nop 1
	v_cndmask_b32_e64 v1, -|v62|, v1, vcc
	v_cmp_gt_i32_e32 vcc, s0, v0
	s_add_i32 s0, s15, 0xfffff141
	s_nop 0
	v_cndmask_b32_e32 v72, 0, v1, vcc
	v_not_b32_e32 v1, v63
	v_cmp_gt_i32_e32 vcc, 0, v63
	s_nop 1
	v_cndmask_b32_e64 v1, -|v63|, v1, vcc
	v_cmp_gt_i32_e32 vcc, s0, v0
	s_add_i32 s0, s15, 0xfffff101
	s_nop 0
	v_cndmask_b32_e32 v71, 0, v1, vcc
	v_not_b32_e32 v1, v64
	v_cmp_gt_i32_e32 vcc, 0, v64
	s_nop 1
	v_cndmask_b32_e64 v1, -|v64|, v1, vcc
	v_cmp_gt_i32_e32 vcc, s0, v0
	s_add_i32 s0, s15, 0xfffff0c1
	s_nop 0
	v_cndmask_b32_e32 v70, 0, v1, vcc
	v_not_b32_e32 v1, v65
	v_cmp_gt_i32_e32 vcc, 0, v65
	s_nop 1
	v_cndmask_b32_e64 v1, -|v65|, v1, vcc
	v_cmp_gt_i32_e32 vcc, s0, v0
	s_add_i32 s0, s15, 0xfffff081
	s_nop 0
	v_cndmask_b32_e32 v69, 0, v1, vcc
	v_not_b32_e32 v1, v66
	v_cmp_gt_i32_e32 vcc, 0, v66
	s_nop 1
	v_cndmask_b32_e64 v1, -|v66|, v1, vcc
	v_cmp_gt_i32_e32 vcc, s0, v0
	s_add_i32 s0, s15, 0xfffff041
	s_nop 0
	v_cndmask_b32_e32 v68, 0, v1, vcc
	v_not_b32_e32 v1, v67
	v_cmp_gt_i32_e32 vcc, 0, v67
	s_nop 1
	v_cndmask_b32_e64 v1, -|v67|, v1, vcc
	v_cmp_gt_i32_e32 vcc, s0, v0
	s_add_i32 s0, s15, 0xfffff001
	s_nop 0
	v_cndmask_b32_e32 v67, 0, v1, vcc
	v_not_b32_e32 v1, v115
	v_cmp_gt_i32_e32 vcc, 0, v115
	s_nop 1
	v_cndmask_b32_e64 v1, -|v115|, v1, vcc
	v_cmp_gt_i32_e32 vcc, s0, v0
	s_add_i32 s0, s15, 0xffffefc1
	s_nop 0
	v_cndmask_b32_e32 v66, 0, v1, vcc
	v_not_b32_e32 v1, v116
	v_cmp_gt_i32_e32 vcc, 0, v116
	s_nop 1
	v_cndmask_b32_e64 v1, -|v116|, v1, vcc
	v_cmp_gt_i32_e32 vcc, s0, v0
	s_add_i32 s0, s15, 0xffffef81
	s_nop 0
	v_cndmask_b32_e32 v65, 0, v1, vcc
	s_waitcnt vmcnt(61)
	v_not_b32_e32 v1, v117
	v_cmp_gt_i32_e32 vcc, 0, v117
	s_nop 1
	v_cndmask_b32_e64 v1, -|v117|, v1, vcc
	v_cmp_gt_i32_e32 vcc, s0, v0
	s_add_i32 s0, s15, 0xffffef41
	s_nop 0
	v_cndmask_b32_e32 v64, 0, v1, vcc
	s_waitcnt vmcnt(60)
	v_not_b32_e32 v1, v118
	v_cmp_gt_i32_e32 vcc, 0, v118
	s_nop 1
	v_cndmask_b32_e64 v1, -|v118|, v1, vcc
	v_cmp_gt_i32_e32 vcc, s0, v0
	s_add_i32 s0, s15, 0xffffef01
	s_nop 0
	v_cndmask_b32_e32 v63, 0, v1, vcc
	s_waitcnt vmcnt(59)
	v_not_b32_e32 v1, v119
	v_cmp_gt_i32_e32 vcc, 0, v119
	s_nop 1
	v_cndmask_b32_e64 v1, -|v119|, v1, vcc
	v_cmp_gt_i32_e32 vcc, s0, v0
	s_add_i32 s0, s15, 0xffffeec1
	s_nop 0
	v_cndmask_b32_e32 v62, 0, v1, vcc
	s_waitcnt vmcnt(58)
	v_not_b32_e32 v1, v120
	v_cmp_gt_i32_e32 vcc, 0, v120
	s_nop 1
	v_cndmask_b32_e64 v1, -|v120|, v1, vcc
	v_cmp_gt_i32_e32 vcc, s0, v0
	s_add_i32 s0, s15, 0xffffee81
	s_nop 0
	v_cndmask_b32_e32 v61, 0, v1, vcc
	s_waitcnt vmcnt(57)
	v_not_b32_e32 v1, v121
	v_cmp_gt_i32_e32 vcc, 0, v121
	s_nop 1
	v_cndmask_b32_e64 v1, -|v121|, v1, vcc
	v_cmp_gt_i32_e32 vcc, s0, v0
	s_add_i32 s0, s15, 0xffffee41
	s_nop 0
	v_cndmask_b32_e32 v60, 0, v1, vcc
	s_waitcnt vmcnt(56)
	v_not_b32_e32 v1, v123
	v_cmp_gt_i32_e32 vcc, 0, v123
	s_nop 1
	v_cndmask_b32_e64 v1, -|v123|, v1, vcc
	v_cmp_gt_i32_e32 vcc, s0, v0
	s_add_i32 s0, s15, 0xffffee01
	s_nop 0
	v_cndmask_b32_e32 v59, 0, v1, vcc
	s_waitcnt vmcnt(55)
	v_not_b32_e32 v1, v122
	v_cmp_gt_i32_e32 vcc, 0, v122
	s_nop 1
	v_cndmask_b32_e64 v1, -|v122|, v1, vcc
	v_cmp_gt_i32_e32 vcc, s0, v0
	s_add_i32 s0, s15, 0xffffedc1
	s_nop 0
	v_cndmask_b32_e32 v58, 0, v1, vcc
	s_waitcnt vmcnt(54)
	v_not_b32_e32 v1, v140
	v_cmp_gt_i32_e32 vcc, 0, v140
	s_nop 1
	v_cndmask_b32_e64 v1, -|v140|, v1, vcc
	v_cmp_gt_i32_e32 vcc, s0, v0
	s_add_i32 s0, s15, 0xffffed81
	s_nop 0
	v_cndmask_b32_e32 v57, 0, v1, vcc
	s_waitcnt vmcnt(53)
	v_not_b32_e32 v1, v141
	v_cmp_gt_i32_e32 vcc, 0, v141
	s_nop 1
	v_cndmask_b32_e64 v1, -|v141|, v1, vcc
	v_cmp_gt_i32_e32 vcc, s0, v0
	s_add_i32 s0, s15, 0xffffed41
	s_nop 0
	v_cndmask_b32_e32 v56, 0, v1, vcc
	s_waitcnt vmcnt(52)
	v_not_b32_e32 v1, v142
	v_cmp_gt_i32_e32 vcc, 0, v142
	s_nop 1
	v_cndmask_b32_e64 v1, -|v142|, v1, vcc
	v_cmp_gt_i32_e32 vcc, s0, v0
	s_add_i32 s0, s15, 0xffffed01
	s_nop 0
	v_cndmask_b32_e32 v55, 0, v1, vcc
	s_waitcnt vmcnt(51)
	v_not_b32_e32 v1, v143
	v_cmp_gt_i32_e32 vcc, 0, v143
	s_nop 1
	v_cndmask_b32_e64 v1, -|v143|, v1, vcc
	v_cmp_gt_i32_e32 vcc, s0, v0
	s_add_i32 s0, s15, 0xffffecc1
	s_nop 0
	v_cndmask_b32_e32 v54, 0, v1, vcc
	s_waitcnt vmcnt(50)
	v_not_b32_e32 v1, v144
	v_cmp_gt_i32_e32 vcc, 0, v144
	s_nop 1
	v_cndmask_b32_e64 v1, -|v144|, v1, vcc
	v_cmp_gt_i32_e32 vcc, s0, v0
	s_add_i32 s0, s15, 0xffffec81
	s_nop 0
	v_cndmask_b32_e32 v53, 0, v1, vcc
	s_waitcnt vmcnt(49)
	v_not_b32_e32 v1, v145
	v_cmp_gt_i32_e32 vcc, 0, v145
	s_nop 1
	v_cndmask_b32_e64 v1, -|v145|, v1, vcc
	v_cmp_gt_i32_e32 vcc, s0, v0
	s_add_i32 s0, s15, 0xffffec41
	s_nop 0
	v_cndmask_b32_e32 v52, 0, v1, vcc
	s_waitcnt vmcnt(48)
	v_not_b32_e32 v1, v147
	v_cmp_gt_i32_e32 vcc, 0, v147
	s_nop 1
	v_cndmask_b32_e64 v1, -|v147|, v1, vcc
	v_cmp_gt_i32_e32 vcc, s0, v0
	s_add_i32 s0, s15, 0xffffec01
	s_nop 0
	v_cndmask_b32_e32 v51, 0, v1, vcc
	s_waitcnt vmcnt(47)
; __device__ __forceinline__ void topk_row(const Params& p, int r, int lane, __attribute__((address_space(3))) int* out) {
;     ...
; #pragma unroll
;     for (int i = 0; i < 128; ++i) {
;       const int lim = n - i * 64;
;       const unsigned u = key[i];
;       key[i] = (lo < lim) ? ((u >> 31) ? ~u : (u | 0x80000000u)) : 0u;
;     }
;     __builtin_amdgcn_sched_barrier(0);
	v_not_b32_e32 v1, v146
	v_cmp_gt_i32_e32 vcc, 0, v146
	s_nop 1
	v_cndmask_b32_e64 v1, -|v146|, v1, vcc
	v_cmp_gt_i32_e32 vcc, s0, v0
	s_add_i32 s0, s15, 0xffffebc1
	s_nop 0
	v_cndmask_b32_e32 v50, 0, v1, vcc
	s_waitcnt vmcnt(46)
	v_not_b32_e32 v1, v148
	v_cmp_gt_i32_e32 vcc, 0, v148
	s_nop 1
	v_cndmask_b32_e64 v1, -|v148|, v1, vcc
	v_cmp_gt_i32_e32 vcc, s0, v0
	s_add_i32 s0, s15, 0xffffeb81
	s_nop 0
	v_cndmask_b32_e32 v49, 0, v1, vcc
	s_waitcnt vmcnt(45)
	v_not_b32_e32 v1, v149
	v_cmp_gt_i32_e32 vcc, 0, v149
	s_nop 1
	v_cndmask_b32_e64 v1, -|v149|, v1, vcc
	v_cmp_gt_i32_e32 vcc, s0, v0
	s_add_i32 s0, s15, 0xffffeb41
	s_nop 0
	v_cndmask_b32_e32 v48, 0, v1, vcc
	s_waitcnt vmcnt(44)
	v_not_b32_e32 v1, v150
	v_cmp_gt_i32_e32 vcc, 0, v150
	s_nop 1
	v_cndmask_b32_e64 v1, -|v150|, v1, vcc
	v_cmp_gt_i32_e32 vcc, s0, v0
	s_add_i32 s0, s15, 0xffffeb01
	s_nop 0
	v_cndmask_b32_e32 v47, 0, v1, vcc
	s_waitcnt vmcnt(43)
	v_not_b32_e32 v1, v151
	v_cmp_gt_i32_e32 vcc, 0, v151
	s_nop 1
	v_cndmask_b32_e64 v1, -|v151|, v1, vcc
	v_cmp_gt_i32_e32 vcc, s0, v0
	s_add_i32 s0, s15, 0xffffeac1
	s_nop 0
	v_cndmask_b32_e32 v46, 0, v1, vcc
	s_waitcnt vmcnt(42)
	v_not_b32_e32 v1, v152
	v_cmp_gt_i32_e32 vcc, 0, v152
	s_nop 1
	v_cndmask_b32_e64 v1, -|v152|, v1, vcc
	v_cmp_gt_i32_e32 vcc, s0, v0
	s_add_i32 s0, s15, 0xffffea81
	s_nop 0
	v_cndmask_b32_e32 v45, 0, v1, vcc
	s_waitcnt vmcnt(41)
	v_not_b32_e32 v1, v153
	v_cmp_gt_i32_e32 vcc, 0, v153
	s_nop 1
	v_cndmask_b32_e64 v1, -|v153|, v1, vcc
	v_cmp_gt_i32_e32 vcc, s0, v0
	s_add_i32 s0, s15, 0xffffea41
	s_nop 0
	v_cndmask_b32_e32 v44, 0, v1, vcc
	s_waitcnt vmcnt(40)
	v_not_b32_e32 v1, v155
	v_cmp_gt_i32_e32 vcc, 0, v155
	s_nop 1
	v_cndmask_b32_e64 v1, -|v155|, v1, vcc
	v_cmp_gt_i32_e32 vcc, s0, v0
	s_add_i32 s0, s15, 0xffffea01
	s_nop 0
	v_cndmask_b32_e32 v43, 0, v1, vcc
	s_waitcnt vmcnt(39)
	v_not_b32_e32 v1, v154
	v_cmp_gt_i32_e32 vcc, 0, v154
	s_nop 1
	v_cndmask_b32_e64 v1, -|v154|, v1, vcc
	v_cmp_gt_i32_e32 vcc, s0, v0
	s_add_i32 s0, s15, 0xffffe9c1
	s_nop 0
	v_cndmask_b32_e32 v42, 0, v1, vcc
	s_waitcnt vmcnt(38)
	v_not_b32_e32 v1, v156
	v_cmp_gt_i32_e32 vcc, 0, v156
	s_nop 1
	v_cndmask_b32_e64 v1, -|v156|, v1, vcc
	v_cmp_gt_i32_e32 vcc, s0, v0
	s_add_i32 s0, s15, 0xffffe981
	s_nop 0
	v_cndmask_b32_e32 v41, 0, v1, vcc
	s_waitcnt vmcnt(37)
	v_not_b32_e32 v1, v157
	v_cmp_gt_i32_e32 vcc, 0, v157
	s_nop 1
	v_cndmask_b32_e64 v1, -|v157|, v1, vcc
	v_cmp_gt_i32_e32 vcc, s0, v0
	s_add_i32 s0, s15, 0xffffe941
	s_nop 0
	v_cndmask_b32_e32 v40, 0, v1, vcc
	s_waitcnt vmcnt(36)
	v_not_b32_e32 v1, v158
	v_cmp_gt_i32_e32 vcc, 0, v158
	s_nop 1
	v_cndmask_b32_e64 v1, -|v158|, v1, vcc
	v_cmp_gt_i32_e32 vcc, s0, v0
	s_add_i32 s0, s15, 0xffffe901
	s_nop 0
	v_cndmask_b32_e32 v39, 0, v1, vcc
	s_waitcnt vmcnt(35)
	v_not_b32_e32 v1, v159
	v_cmp_gt_i32_e32 vcc, 0, v159
	s_nop 1
	v_cndmask_b32_e64 v1, -|v159|, v1, vcc
	v_cmp_gt_i32_e32 vcc, s0, v0
	s_add_i32 s0, s15, 0xffffe8c1
	s_nop 0
	v_cndmask_b32_e32 v38, 0, v1, vcc
	s_waitcnt vmcnt(34)
	v_not_b32_e32 v1, v160
	v_cmp_gt_i32_e32 vcc, 0, v160
	s_nop 1
	v_cndmask_b32_e64 v1, -|v160|, v1, vcc
	v_cmp_gt_i32_e32 vcc, s0, v0
	s_add_i32 s0, s15, 0xffffe881
	s_nop 0
	v_cndmask_b32_e32 v37, 0, v1, vcc
	s_waitcnt vmcnt(33)
	v_not_b32_e32 v1, v161
	v_cmp_gt_i32_e32 vcc, 0, v161
	s_nop 1
	v_cndmask_b32_e64 v1, -|v161|, v1, vcc
	v_cmp_gt_i32_e32 vcc, s0, v0
	s_add_i32 s0, s15, 0xffffe841
	s_nop 0
	v_cndmask_b32_e32 v36, 0, v1, vcc
	s_waitcnt vmcnt(32)
	v_not_b32_e32 v1, v163
	v_cmp_gt_i32_e32 vcc, 0, v163
	s_nop 1
	v_cndmask_b32_e64 v1, -|v163|, v1, vcc
	v_cmp_gt_i32_e32 vcc, s0, v0
	s_add_i32 s0, s15, 0xffffe801
	s_nop 0
	v_cndmask_b32_e32 v35, 0, v1, vcc
	s_waitcnt vmcnt(31)
	v_not_b32_e32 v1, v162
	v_cmp_gt_i32_e32 vcc, 0, v162
	s_nop 1
	v_cndmask_b32_e64 v1, -|v162|, v1, vcc
	v_cmp_gt_i32_e32 vcc, s0, v0
	s_add_i32 s0, s15, 0xffffe7c1
	s_nop 0
	v_cndmask_b32_e32 v34, 0, v1, vcc
	s_waitcnt vmcnt(30)
	v_not_b32_e32 v1, v164
	v_cmp_gt_i32_e32 vcc, 0, v164
	s_nop 1
	v_cndmask_b32_e64 v1, -|v164|, v1, vcc
	v_cmp_gt_i32_e32 vcc, s0, v0
	s_add_i32 s0, s15, 0xffffe781
	s_nop 0
	v_cndmask_b32_e32 v32, 0, v1, vcc
	s_waitcnt vmcnt(29)
	v_not_b32_e32 v1, v165
	v_cmp_gt_i32_e32 vcc, 0, v165
	s_nop 1
	v_cndmask_b32_e64 v1, -|v165|, v1, vcc
	v_cmp_gt_i32_e32 vcc, s0, v0
	s_add_i32 s0, s15, 0xffffe741
	s_nop 0
	v_cndmask_b32_e32 v31, 0, v1, vcc
	s_waitcnt vmcnt(28)
	v_not_b32_e32 v1, v166
	v_cmp_gt_i32_e32 vcc, 0, v166
	s_nop 1
	v_cndmask_b32_e64 v1, -|v166|, v1, vcc
	v_cmp_gt_i32_e32 vcc, s0, v0
	s_add_i32 s0, s15, 0xffffe701
	s_nop 0
	v_cndmask_b32_e32 v30, 0, v1, vcc
	s_waitcnt vmcnt(27)
	v_not_b32_e32 v1, v167
	v_cmp_gt_i32_e32 vcc, 0, v167
	s_nop 1
	v_cndmask_b32_e64 v1, -|v167|, v1, vcc
	v_cmp_gt_i32_e32 vcc, s0, v0
	s_add_i32 s0, s15, 0xffffe6c1
	s_nop 0
	v_cndmask_b32_e32 v29, 0, v1, vcc
	s_waitcnt vmcnt(26)
	v_not_b32_e32 v1, v168
	v_cmp_gt_i32_e32 vcc, 0, v168
	s_nop 1
	v_cndmask_b32_e64 v1, -|v168|, v1, vcc
	v_cmp_gt_i32_e32 vcc, s0, v0
	s_add_i32 s0, s15, 0xffffe681
	s_nop 0
	v_cndmask_b32_e32 v28, 0, v1, vcc
	s_waitcnt vmcnt(25)
	v_not_b32_e32 v1, v169
	v_cmp_gt_i32_e32 vcc, 0, v169
	s_nop 1
	v_cndmask_b32_e64 v1, -|v169|, v1, vcc
	v_cmp_gt_i32_e32 vcc, s0, v0
	s_add_i32 s0, s15, 0xffffe641
	s_nop 0
	v_cndmask_b32_e32 v27, 0, v1, vcc
	s_waitcnt vmcnt(24)
	v_not_b32_e32 v1, v171
	v_cmp_gt_i32_e32 vcc, 0, v171
	s_nop 1
	v_cndmask_b32_e64 v1, -|v171|, v1, vcc
	v_cmp_gt_i32_e32 vcc, s0, v0
	s_add_i32 s0, s15, 0xffffe601
	s_nop 0
	v_cndmask_b32_e32 v26, 0, v1, vcc
	s_waitcnt vmcnt(23)
	v_not_b32_e32 v1, v170
	v_cmp_gt_i32_e32 vcc, 0, v170
	s_nop 1
	v_cndmask_b32_e64 v1, -|v170|, v1, vcc
	v_cmp_gt_i32_e32 vcc, s0, v0
	s_add_i32 s0, s15, 0xffffe5c1
	s_nop 0
	v_cndmask_b32_e32 v25, 0, v1, vcc
	s_waitcnt vmcnt(22)
; __device__ __forceinline__ void topk_row(const Params& p, int r, int lane, __attribute__((address_space(3))) int* out) {
;     ...
; #pragma unroll
;     for (int i = 0; i < 128; ++i) {
;       const int lim = n - i * 64;
;       const unsigned u = key[i];
;       key[i] = (lo < lim) ? ((u >> 31) ? ~u : (u | 0x80000000u)) : 0u;
;     }
;     __builtin_amdgcn_sched_barrier(0);
;     unsigned Tv = 0u;
;     bool exact = false;
;     ...
;       const unsigned cand = Tv | (1u << bit);
;       int c = 0;
; #pragma unroll
;       for (int blk = 0; blk < 8; ++blk) {
;         if (blk * 16 < nch) {
; #pragma unroll
;           for (int ii = 0; ii < 16; ++ii) c += (key[blk * 16 + ii] >= cand) ? 1 : 0;
	v_not_b32_e32 v1, v172
	v_cmp_gt_i32_e32 vcc, 0, v172
	s_nop 1
	v_cndmask_b32_e64 v1, -|v172|, v1, vcc
	v_cmp_gt_i32_e32 vcc, s0, v0
	s_add_i32 s0, s15, 0xffffe581
	s_nop 0
	v_cndmask_b32_e32 v24, 0, v1, vcc
	s_waitcnt vmcnt(21)
	v_not_b32_e32 v1, v173
	v_cmp_gt_i32_e32 vcc, 0, v173
	s_nop 1
	v_cndmask_b32_e64 v1, -|v173|, v1, vcc
	v_cmp_gt_i32_e32 vcc, s0, v0
	s_add_i32 s0, s15, 0xffffe541
	s_nop 0
	v_cndmask_b32_e32 v23, 0, v1, vcc
	s_waitcnt vmcnt(20)
	v_not_b32_e32 v1, v174
	v_cmp_gt_i32_e32 vcc, 0, v174
	s_nop 1
	v_cndmask_b32_e64 v1, -|v174|, v1, vcc
	v_cmp_gt_i32_e32 vcc, s0, v0
	s_add_i32 s0, s15, 0xffffe501
	s_nop 0
	v_cndmask_b32_e32 v22, 0, v1, vcc
	s_waitcnt vmcnt(19)
	v_not_b32_e32 v1, v175
	v_cmp_gt_i32_e32 vcc, 0, v175
	s_nop 1
	v_cndmask_b32_e64 v1, -|v175|, v1, vcc
	v_cmp_gt_i32_e32 vcc, s0, v0
	s_add_i32 s0, s15, 0xffffe4c1
	s_nop 0
	v_cndmask_b32_e32 v21, 0, v1, vcc
	s_waitcnt vmcnt(18)
	v_not_b32_e32 v1, v176
	v_cmp_gt_i32_e32 vcc, 0, v176
	s_nop 1
	v_cndmask_b32_e64 v1, -|v176|, v1, vcc
	v_cmp_gt_i32_e32 vcc, s0, v0
	s_add_i32 s0, s15, 0xffffe481
	s_nop 0
	v_cndmask_b32_e32 v20, 0, v1, vcc
	s_waitcnt vmcnt(17)
	v_not_b32_e32 v1, v177
	v_cmp_gt_i32_e32 vcc, 0, v177
	s_nop 1
	v_cndmask_b32_e64 v1, -|v177|, v1, vcc
	v_cmp_gt_i32_e32 vcc, s0, v0
	s_add_i32 s0, s15, 0xffffe441
	s_nop 0
	v_cndmask_b32_e32 v19, 0, v1, vcc
	s_waitcnt vmcnt(16)
	v_not_b32_e32 v1, v179
	v_cmp_gt_i32_e32 vcc, 0, v179
	s_nop 1
	v_cndmask_b32_e64 v1, -|v179|, v1, vcc
	v_cmp_gt_i32_e32 vcc, s0, v0
	s_add_i32 s0, s15, 0xffffe401
	s_nop 0
	v_cndmask_b32_e32 v18, 0, v1, vcc
	s_waitcnt vmcnt(15)
	v_not_b32_e32 v1, v178
	v_cmp_gt_i32_e32 vcc, 0, v178
	s_nop 1
	v_cndmask_b32_e64 v1, -|v178|, v1, vcc
	v_cmp_gt_i32_e32 vcc, s0, v0
	s_add_i32 s0, s15, 0xffffe3c1
	s_nop 0
	v_cndmask_b32_e32 v17, 0, v1, vcc
	s_waitcnt vmcnt(14)
	v_not_b32_e32 v1, v180
	v_cmp_gt_i32_e32 vcc, 0, v180
	s_nop 1
	v_cndmask_b32_e64 v1, -|v180|, v1, vcc
	v_cmp_gt_i32_e32 vcc, s0, v0
	s_add_i32 s0, s15, 0xffffe381
	s_nop 0
	v_cndmask_b32_e32 v16, 0, v1, vcc
	s_waitcnt vmcnt(13)
	v_not_b32_e32 v1, v181
	v_cmp_gt_i32_e32 vcc, 0, v181
	s_nop 1
	v_cndmask_b32_e64 v1, -|v181|, v1, vcc
	v_cmp_gt_i32_e32 vcc, s0, v0
	s_add_i32 s0, s15, 0xffffe341
	s_nop 0
	v_cndmask_b32_e32 v15, 0, v1, vcc
	s_waitcnt vmcnt(12)
	v_not_b32_e32 v1, v182
	v_cmp_gt_i32_e32 vcc, 0, v182
	s_nop 1
	v_cndmask_b32_e64 v1, -|v182|, v1, vcc
	v_cmp_gt_i32_e32 vcc, s0, v0
	s_add_i32 s0, s15, 0xffffe301
	s_nop 0
	v_cndmask_b32_e32 v14, 0, v1, vcc
	s_waitcnt vmcnt(11)
	v_not_b32_e32 v1, v183
	v_cmp_gt_i32_e32 vcc, 0, v183
	s_nop 1
	v_cndmask_b32_e64 v1, -|v183|, v1, vcc
	v_cmp_gt_i32_e32 vcc, s0, v0
	s_add_i32 s0, s15, 0xffffe2c1
	s_nop 0
	v_cndmask_b32_e32 v13, 0, v1, vcc
	s_waitcnt vmcnt(10)
	v_not_b32_e32 v1, v184
	v_cmp_gt_i32_e32 vcc, 0, v184
	s_nop 1
	v_cndmask_b32_e64 v1, -|v184|, v1, vcc
	v_cmp_gt_i32_e32 vcc, s0, v0
	s_add_i32 s0, s15, 0xffffe281
	s_nop 0
	v_cndmask_b32_e32 v12, 0, v1, vcc
	s_waitcnt vmcnt(9)
	v_not_b32_e32 v1, v185
	v_cmp_gt_i32_e32 vcc, 0, v185
	s_nop 1
	v_cndmask_b32_e64 v1, -|v185|, v1, vcc
	v_cmp_gt_i32_e32 vcc, s0, v0
	s_add_i32 s0, s15, 0xffffe241
	s_nop 0
	v_cndmask_b32_e32 v11, 0, v1, vcc
	s_waitcnt vmcnt(8)
	v_not_b32_e32 v1, v187
	v_cmp_gt_i32_e32 vcc, 0, v187
	s_nop 1
	v_cndmask_b32_e64 v1, -|v187|, v1, vcc
	v_cmp_gt_i32_e32 vcc, s0, v0
	s_add_i32 s0, s15, 0xffffe201
	s_nop 0
	v_cndmask_b32_e32 v10, 0, v1, vcc
	s_waitcnt vmcnt(7)
	v_not_b32_e32 v1, v186
	v_cmp_gt_i32_e32 vcc, 0, v186
	s_nop 1
	v_cndmask_b32_e64 v1, -|v186|, v1, vcc
	v_cmp_gt_i32_e32 vcc, s0, v0
	s_add_i32 s0, s15, 0xffffe1c1
	s_nop 0
	v_cndmask_b32_e32 v9, 0, v1, vcc
	s_waitcnt vmcnt(6)
	v_not_b32_e32 v1, v188
	v_cmp_gt_i32_e32 vcc, 0, v188
	s_nop 1
	v_cndmask_b32_e64 v1, -|v188|, v1, vcc
	v_cmp_gt_i32_e32 vcc, s0, v0
	s_add_i32 s0, s15, 0xffffe181
	s_nop 0
	v_cndmask_b32_e32 v8, 0, v1, vcc
	s_waitcnt vmcnt(5)
	v_not_b32_e32 v1, v189
	v_cmp_gt_i32_e32 vcc, 0, v189
	s_nop 1
	v_cndmask_b32_e64 v1, -|v189|, v1, vcc
	v_cmp_gt_i32_e32 vcc, s0, v0
	s_add_i32 s0, s15, 0xffffe141
	s_nop 0
	v_cndmask_b32_e32 v7, 0, v1, vcc
	s_waitcnt vmcnt(4)
	v_not_b32_e32 v1, v190
	v_cmp_gt_i32_e32 vcc, 0, v190
	s_nop 1
	v_cndmask_b32_e64 v1, -|v190|, v1, vcc
	v_cmp_gt_i32_e32 vcc, s0, v0
	s_add_i32 s0, s15, 0xffffe101
	s_nop 0
	v_cndmask_b32_e32 v6, 0, v1, vcc
	s_waitcnt vmcnt(3)
	v_not_b32_e32 v1, v191
	v_cmp_gt_i32_e32 vcc, 0, v191
	s_nop 1
	v_cndmask_b32_e64 v1, -|v191|, v1, vcc
	v_cmp_gt_i32_e32 vcc, s0, v0
	s_add_i32 s0, s15, 0xffffe0c1
	s_nop 0
	v_cndmask_b32_e32 v5, 0, v1, vcc
	s_waitcnt vmcnt(2)
	v_not_b32_e32 v1, v192
	v_cmp_gt_i32_e32 vcc, 0, v192
	s_nop 1
	v_cndmask_b32_e64 v1, -|v192|, v1, vcc
	v_cmp_gt_i32_e32 vcc, s0, v0
	s_add_i32 s0, s15, 0xffffe081
	s_nop 0
	v_cndmask_b32_e32 v3, 0, v1, vcc
	s_waitcnt vmcnt(1)
	v_not_b32_e32 v1, v193
	v_cmp_gt_i32_e32 vcc, 0, v193
	s_nop 1
	v_cndmask_b32_e64 v1, -|v193|, v1, vcc
	v_cmp_gt_i32_e32 vcc, s0, v0
	s_add_i32 s0, s15, 0xffffe041
	s_nop 0
	v_cndmask_b32_e32 v2, 0, v1, vcc
	s_waitcnt vmcnt(0)
	v_not_b32_e32 v1, v194
	v_cmp_gt_i32_e32 vcc, 0, v194
	s_nop 1
	v_cndmask_b32_e64 v1, -|v194|, v1, vcc
	v_cmp_gt_i32_e32 vcc, s0, v0
	s_nop 1
	v_cndmask_b32_e32 v1, 0, v1, vcc
	s_cmpk_gt_u32 s15, 0x3ff
	s_cselect_b64 s[0:1], -1, 0
	s_cmpk_gt_u32 s15, 0x7ff
	s_cselect_b64 s[52:53], -1, 0
	s_cmpk_gt_u32 s15, 0xbff
	s_cselect_b64 s[54:55], -1, 0
	s_cmpk_gt_u32 s15, 0xfff
	s_cselect_b64 s[56:57], -1, 0
	s_cmpk_gt_u32 s15, 0x13ff
	s_cselect_b64 s[58:59], -1, 0
	s_cmpk_gt_u32 s15, 0x17ff
	s_cselect_b64 s[60:61], -1, 0
	s_cmpk_gt_u32 s15, 0x1bff
	s_cselect_b64 s[62:63], -1, 0
	v_mov_b32_e32 v140, 31
	v_mov_b32_e32 v123, 0
	v_cndmask_b32_e64 v142, 0, 1, s[54:55]
	v_cmp_ne_u32_e64 s[64:65], 1, v142
	s_nop 3
	v_writelane_b32 v244, s64, 2
	v_writelane_b32 v244, s65, 3
	v_cndmask_b32_e64 v142, 0, 1, s[56:57]
	v_cmp_ne_u32_e64 s[64:65], 1, v142
	s_nop 3
	v_writelane_b32 v244, s64, 4
	v_writelane_b32 v244, s65, 5
	v_cndmask_b32_e64 v142, 0, 1, s[58:59]
	v_cmp_ne_u32_e64 s[64:65], 1, v142
	s_nop 3
	v_writelane_b32 v244, s64, 6
	v_writelane_b32 v244, s65, 7
	v_cndmask_b32_e64 v142, 0, 1, s[60:61]
	v_cmp_ne_u32_e64 s[64:65], 1, v142
	s_nop 3
	v_writelane_b32 v244, s64, 8
	v_writelane_b32 v244, s65, 9
	v_cndmask_b32_e64 v142, 0, 1, s[62:63]
	v_cmp_ne_u32_e64 s[64:65], 1, v142
	s_nop 3
	v_writelane_b32 v244, s64, 10
	v_writelane_b32 v244, s65, 11
	s_branch .LBB0_74

; __device__ __forceinline__ void ph_indexer(const Params& p, char* shm) {
;     ...
;           IDX_TILE(ktp * 2, pr0);
;           __builtin_amdgcn_sched_barrier(0);
;           IDX_TILE(ktp * 2 + 1, pr1);
;           __builtin_amdgcn_sched_barrier(0);
;     ...
; #pragma unroll
;           for (int q = 0; q < 2; ++q) {
;             const float mine = half ? pr1[q] : pr0[q];
;             const float send = half ? pr0[q] : pr1[q];
;             const float recv = __shfl_xor(send, 32);
;             p.SC[(rowb + wid * 2 + q) * L + st * 128 + ktp * 64 + lane] = mine + recv;
;           }
.LBB0_928:
	s_lshl_b32 s3, s4, 15
	v_cmp_lt_i32_e32 vcc, v209, v208
	s_and_b32 s3, s3, 0x8000
	s_lshl_b32 s4, s4, 7
	v_cndmask_b32_e32 v0, v207, v209, vcc
	v_or_b32_e32 v129, s3, v117
	v_lshlrev_b32_e32 v119, 2, v0
	v_lshl_add_u64 v[138:139], s[4:5], 2, v[124:125]
	ds_read_b128 v[172:175], v129
	ds_read_b128 v[176:179], v129 offset:256
	ds_read_b128 v[180:183], v129 offset:2048
	ds_read_b128 v[184:187], v129 offset:2304
	ds_read_b128 v[188:191], v129 offset:4096
	ds_read_b128 v[192:195], v129 offset:4352
	ds_read_b128 v[196:199], v129 offset:6144
	ds_read_b128 v[226:229], v129 offset:6400
	s_waitcnt lgkmcnt(8)
	v_cvt_f32_f16_e32 v140, v34
	v_cvt_f32_f16_sdwa v141, v34 dst_sel:DWORD dst_unused:UNUSED_PAD src0_sel:WORD_1
	v_cvt_f32_f16_e32 v142, v35
	v_cvt_f32_f16_sdwa v143, v35 dst_sel:DWORD dst_unused:UNUSED_PAD src0_sel:WORD_1
	v_cvt_f32_f16_e32 v144, v36
	v_cvt_f32_f16_sdwa v145, v36 dst_sel:DWORD dst_unused:UNUSED_PAD src0_sel:WORD_1
	v_cvt_f32_f16_e32 v146, v37
	v_cvt_f32_f16_sdwa v147, v37 dst_sel:DWORD dst_unused:UNUSED_PAD src0_sel:WORD_1
	v_cvt_f32_f16_e32 v148, v38
	v_cvt_f32_f16_sdwa v149, v38 dst_sel:DWORD dst_unused:UNUSED_PAD src0_sel:WORD_1
	v_cvt_f32_f16_e32 v150, v39
	v_cvt_f32_f16_sdwa v151, v39 dst_sel:DWORD dst_unused:UNUSED_PAD src0_sel:WORD_1
	v_cvt_f32_f16_e32 v152, v40
	v_cvt_f32_f16_sdwa v153, v40 dst_sel:DWORD dst_unused:UNUSED_PAD src0_sel:WORD_1
	v_cvt_f32_f16_e32 v154, v41
	v_cvt_f32_f16_sdwa v155, v41 dst_sel:DWORD dst_unused:UNUSED_PAD src0_sel:WORD_1
	s_cmp_eq_u32 s22, 1
	s_cbranch_scc1 .Lidx_first_s0
	s_waitcnt lgkmcnt(7)
	v_mfma_f32_16x16x32_bf16 v[0:3], v[74:77], v[172:175], 0
	v_max_i32_e32 v230, 0, v16
	v_fma_f32 v220, v230, v148, 0
	v_max_i32_e32 v231, 0, v17
	v_mfma_f32_16x16x32_bf16 v[8:11], v[62:65], v[172:175], 0
	v_fmac_f32_e32 v220, v231, v149
	v_max_i32_e32 v230, 0, v18
	v_fmac_f32_e32 v220, v230, v150
	s_waitcnt lgkmcnt(6)
	v_mfma_f32_16x16x32_bf16 v[4:7], v[74:77], v[176:179], 0
	v_max_i32_e32 v231, 0, v19
	v_fmac_f32_e32 v220, v231, v151
	v_max_i32_e32 v230, 0, v24
	v_mfma_f32_16x16x32_bf16 v[12:15], v[62:65], v[176:179], 0
	v_fmac_f32_e32 v220, v230, v152
	v_max_i32_e32 v231, 0, v25
	v_fmac_f32_e32 v220, v231, v153
	s_waitcnt lgkmcnt(5)
	v_mfma_f32_16x16x32_bf16 v[0:3], v[50:53], v[180:183], v[0:3]
	v_max_i32_e32 v230, 0, v26
	v_fmac_f32_e32 v220, v230, v154
	v_max_i32_e32 v231, 0, v27
	v_mfma_f32_16x16x32_bf16 v[8:11], v[66:69], v[180:183], v[8:11]
	v_fmac_f32_e32 v220, v231, v155
	v_max_i32_e32 v230, 0, v20
	v_fma_f32 v221, v230, v148, 0
	s_waitcnt lgkmcnt(4)
	v_mfma_f32_16x16x32_bf16 v[4:7], v[50:53], v[184:187], v[4:7]
	v_max_i32_e32 v231, 0, v21
	v_fmac_f32_e32 v221, v231, v149
	v_max_i32_e32 v230, 0, v22
	v_mfma_f32_16x16x32_bf16 v[12:15], v[66:69], v[184:187], v[12:15]
	v_fmac_f32_e32 v221, v230, v150
	v_max_i32_e32 v231, 0, v23
	v_fmac_f32_e32 v221, v231, v151
	s_waitcnt lgkmcnt(3)
	v_mfma_f32_16x16x32_bf16 v[0:3], v[54:57], v[188:191], v[0:3]
	v_max_i32_e32 v230, 0, v28
	v_fmac_f32_e32 v221, v230, v152
	v_max_i32_e32 v231, 0, v29
	v_mfma_f32_16x16x32_bf16 v[8:11], v[70:73], v[188:191], v[8:11]
	v_fmac_f32_e32 v221, v231, v153
	v_max_i32_e32 v230, 0, v30
	v_fmac_f32_e32 v221, v230, v154
	s_waitcnt lgkmcnt(2)
	v_mfma_f32_16x16x32_bf16 v[4:7], v[54:57], v[192:195], v[4:7]
	v_max_i32_e32 v231, 0, v31
	v_fmac_f32_e32 v221, v231, v155
	s_nop 1
	v_mfma_f32_16x16x32_bf16 v[12:15], v[70:73], v[192:195], v[12:15]
	v_permlane16_swap_b32_e32 v222, v223
	v_permlane16_swap_b32_e32 v218, v219
	v_permlane16_swap_b32_e32 v202, v203
	s_waitcnt lgkmcnt(1)
	v_mfma_f32_16x16x32_bf16 v[0:3], v[58:61], v[196:199], v[0:3]
	v_permlane16_swap_b32_e32 v220, v221
	v_add_f32_e32 v222, v222, v223
	v_add_f32_e32 v218, v218, v219
	v_mfma_f32_16x16x32_bf16 v[8:11], v[78:81], v[196:199], v[8:11]
	v_add_f32_e32 v202, v202, v203
	v_add_f32_e32 v220, v220, v221
	s_nop 1
	s_waitcnt lgkmcnt(0)
	v_mfma_f32_16x16x32_bf16 v[4:7], v[58:61], v[226:229], v[4:7]
	v_permlane32_swap_b32_e32 v222, v218
	v_permlane32_swap_b32_e32 v202, v220
	v_add_f32_e32 v222, v222, v218
	v_mfma_f32_16x16x32_bf16 v[12:15], v[78:81], v[226:229], v[12:15]
	v_add_f32_e32 v202, v202, v220
	global_store_dword v[232:233], v222, off offset:256 nt
	global_store_dword v[234:235], v202, off offset:256 nt
	s_branch .Lidx_join_s0

; __device__ __forceinline__ void ph_indexer(const Params& p, char* shm) {
;     ...
;           IDX_TILE(ktp * 2, pr0);
;           __builtin_amdgcn_sched_barrier(0);
;           IDX_TILE(ktp * 2 + 1, pr1);
;           __builtin_amdgcn_sched_barrier(0);
.Lidx_nostage_s0_3:
	v_max_i32_e32 v225, 0, v1
	v_fmac_f32_e32 v200, v225, v141
	v_mfma_f32_16x16x32_bf16 v[20:23], v[82:85], v[184:187], v[20:23]
	v_max_i32_e32 v224, 0, v2
	v_fmac_f32_e32 v200, v224, v142
	v_max_i32_e32 v225, 0, v3
	v_mfma_f32_16x16x32_bf16 v[28:31], v[98:101], v[184:187], v[28:31]
	ds_read_b128 v[184:187], v129 offset:10496
	v_fmac_f32_e32 v200, v225, v143
	v_max_i32_e32 v224, 0, v8
	v_fmac_f32_e32 v200, v224, v144
	v_mfma_f32_16x16x32_bf16 v[16:19], v[86:89], v[188:191], v[16:19]
	v_max_i32_e32 v225, 0, v9
	v_fmac_f32_e32 v200, v225, v145
	v_max_i32_e32 v224, 0, v10
	v_mfma_f32_16x16x32_bf16 v[24:27], v[102:105], v[188:191], v[24:27]
	ds_read_b128 v[188:191], v129 offset:12288
	v_fmac_f32_e32 v200, v224, v146
	v_max_i32_e32 v225, 0, v11
	v_fmac_f32_e32 v200, v225, v147
	v_mfma_f32_16x16x32_bf16 v[20:23], v[86:89], v[192:195], v[20:23]
	v_max_i32_e32 v224, 0, v4
	v_fma_f32 v201, v224, v140, 0
	v_max_i32_e32 v225, 0, v5
	v_mfma_f32_16x16x32_bf16 v[28:31], v[102:105], v[192:195], v[28:31]
	ds_read_b128 v[192:195], v129 offset:12544
	v_fmac_f32_e32 v201, v225, v141
	v_max_i32_e32 v224, 0, v6
	v_fmac_f32_e32 v201, v224, v142
	v_mfma_f32_16x16x32_bf16 v[16:19], v[90:93], v[196:199], v[16:19]
	v_max_i32_e32 v225, 0, v7
	v_fmac_f32_e32 v201, v225, v143
	v_max_i32_e32 v224, 0, v12
	v_mfma_f32_16x16x32_bf16 v[24:27], v[110:113], v[196:199], v[24:27]
	ds_read_b128 v[196:199], v129 offset:14336
	v_fmac_f32_e32 v201, v224, v144
	v_max_i32_e32 v225, 0, v13
	v_fmac_f32_e32 v201, v225, v145
	v_mfma_f32_16x16x32_bf16 v[20:23], v[90:93], v[226:229], v[20:23]
	v_max_i32_e32 v224, 0, v14
	v_fmac_f32_e32 v201, v224, v146
	v_mfma_f32_16x16x32_bf16 v[28:31], v[110:113], v[226:229], v[28:31]
	ds_read_b128 v[226:229], v129 offset:14592
	v_max_i32_e32 v225, 0, v15
	v_fmac_f32_e32 v201, v225, v147
	s_waitcnt lgkmcnt(7)
	v_mfma_f32_16x16x32_bf16 v[0:3], v[74:77], v[172:175], 0
	v_mfma_f32_16x16x32_bf16 v[8:11], v[62:65], v[172:175], 0
	s_waitcnt lgkmcnt(6)
	v_mfma_f32_16x16x32_bf16 v[4:7], v[74:77], v[176:179], 0
	v_mfma_f32_16x16x32_bf16 v[12:15], v[62:65], v[176:179], 0
	v_max_i32_e32 v230, 0, v16
	v_fma_f32 v202, v230, v148, 0
	s_waitcnt lgkmcnt(5)
	v_mfma_f32_16x16x32_bf16 v[0:3], v[50:53], v[180:183], v[0:3]
	v_max_i32_e32 v231, 0, v17
	v_fmac_f32_e32 v202, v231, v149
	v_mfma_f32_16x16x32_bf16 v[8:11], v[66:69], v[180:183], v[8:11]
	v_max_i32_e32 v230, 0, v18
	v_fmac_f32_e32 v202, v230, v150
	s_waitcnt lgkmcnt(4)
	v_mfma_f32_16x16x32_bf16 v[4:7], v[50:53], v[184:187], v[4:7]
	v_max_i32_e32 v231, 0, v19
	v_fmac_f32_e32 v202, v231, v151
	v_mfma_f32_16x16x32_bf16 v[12:15], v[66:69], v[184:187], v[12:15]
	v_max_i32_e32 v230, 0, v24
	v_fmac_f32_e32 v202, v230, v152
	s_waitcnt lgkmcnt(3)
	v_mfma_f32_16x16x32_bf16 v[0:3], v[54:57], v[188:191], v[0:3]
	v_max_i32_e32 v231, 0, v25
	v_fmac_f32_e32 v202, v231, v153
	v_mfma_f32_16x16x32_bf16 v[8:11], v[70:73], v[188:191], v[8:11]
	v_max_i32_e32 v230, 0, v26
	v_fmac_f32_e32 v202, v230, v154
	v_max_i32_e32 v231, 0, v27
	s_waitcnt lgkmcnt(2)
	v_mfma_f32_16x16x32_bf16 v[4:7], v[54:57], v[192:195], v[4:7]
	v_fmac_f32_e32 v202, v231, v155
	v_max_i32_e32 v230, 0, v20
	v_fma_f32 v203, v230, v148, 0
	v_mfma_f32_16x16x32_bf16 v[12:15], v[70:73], v[192:195], v[12:15]
	v_max_i32_e32 v231, 0, v21
	v_fmac_f32_e32 v203, v231, v149
	v_max_i32_e32 v230, 0, v22
	s_waitcnt lgkmcnt(1)
	v_mfma_f32_16x16x32_bf16 v[0:3], v[58:61], v[196:199], v[0:3]
	v_fmac_f32_e32 v203, v230, v150
	v_max_i32_e32 v231, 0, v23
	v_fmac_f32_e32 v203, v231, v151
	v_mfma_f32_16x16x32_bf16 v[8:11], v[78:81], v[196:199], v[8:11]
	v_max_i32_e32 v230, 0, v28
	v_fmac_f32_e32 v203, v230, v152
	v_max_i32_e32 v231, 0, v29
	s_waitcnt lgkmcnt(0)
	v_mfma_f32_16x16x32_bf16 v[4:7], v[58:61], v[226:229], v[4:7]
	v_fmac_f32_e32 v203, v231, v153
	v_max_i32_e32 v230, 0, v30
	v_fmac_f32_e32 v203, v230, v154
	v_mfma_f32_16x16x32_bf16 v[12:15], v[78:81], v[226:229], v[12:15]
	v_max_i32_e32 v231, 0, v31
	v_fmac_f32_e32 v203, v231, v155
	v_mfma_f32_16x16x32_bf16 v[16:19], v[106:109], v[172:175], 0
	v_mfma_f32_16x16x32_bf16 v[24:27], v[94:97], v[172:175], 0
	ds_read_b128 v[172:175], v129 offset:16384
	v_mfma_f32_16x16x32_bf16 v[20:23], v[106:109], v[176:179], 0
	v_mfma_f32_16x16x32_bf16 v[28:31], v[94:97], v[176:179], 0
	ds_read_b128 v[176:179], v129 offset:16640
	v_mfma_f32_16x16x32_bf16 v[16:19], v[82:85], v[180:183], v[16:19]
	v_max_i32_e32 v224, 0, v0
	v_fma_f32 v218, v224, v140, 0
	v_mfma_f32_16x16x32_bf16 v[24:27], v[98:101], v[180:183], v[24:27]
	ds_read_b128 v[180:183], v129 offset:18432
	v_max_i32_e32 v225, 0, v1
	v_fmac_f32_e32 v218, v225, v141
	v_mfma_f32_16x16x32_bf16 v[20:23], v[82:85], v[184:187], v[20:23]
	v_max_i32_e32 v224, 0, v2
	v_fmac_f32_e32 v218, v224, v142
	v_max_i32_e32 v225, 0, v3
	v_mfma_f32_16x16x32_bf16 v[28:31], v[98:101], v[184:187], v[28:31]
	ds_read_b128 v[184:187], v129 offset:18688
	v_fmac_f32_e32 v218, v225, v143
	v_max_i32_e32 v224, 0, v8
	v_fmac_f32_e32 v218, v224, v144
	v_mfma_f32_16x16x32_bf16 v[16:19], v[86:89], v[188:191], v[16:19]
	v_max_i32_e32 v225, 0, v9
	v_fmac_f32_e32 v218, v225, v145
	v_max_i32_e32 v224, 0, v10
	v_mfma_f32_16x16x32_bf16 v[24:27], v[102:105], v[188:191], v[24:27]
	ds_read_b128 v[188:191], v129 offset:20480
	v_fmac_f32_e32 v218, v224, v146
	v_max_i32_e32 v225, 0, v11
	v_fmac_f32_e32 v218, v225, v147
	v_mfma_f32_16x16x32_bf16 v[20:23], v[86:89], v[192:195], v[20:23]
	v_max_i32_e32 v224, 0, v4
	v_fma_f32 v219, v224, v140, 0
	v_max_i32_e32 v225, 0, v5
	v_mfma_f32_16x16x32_bf16 v[28:31], v[102:105], v[192:195], v[28:31]
	ds_read_b128 v[192:195], v129 offset:20736
	v_fmac_f32_e32 v219, v225, v141
	v_max_i32_e32 v224, 0, v6
	v_fmac_f32_e32 v219, v224, v142
	v_mfma_f32_16x16x32_bf16 v[16:19], v[90:93], v[196:199], v[16:19]
	v_max_i32_e32 v225, 0, v7
	v_fmac_f32_e32 v219, v225, v143
	v_max_i32_e32 v224, 0, v12
	v_mfma_f32_16x16x32_bf16 v[24:27], v[110:113], v[196:199], v[24:27]
	ds_read_b128 v[196:199], v129 offset:22528
	v_fmac_f32_e32 v219, v224, v144
	v_max_i32_e32 v225, 0, v13
	v_fmac_f32_e32 v219, v225, v145
	v_mfma_f32_16x16x32_bf16 v[20:23], v[90:93], v[226:229], v[20:23]
	v_max_i32_e32 v224, 0, v14
	v_fmac_f32_e32 v219, v224, v146
	v_mfma_f32_16x16x32_bf16 v[28:31], v[110:113], v[226:229], v[28:31]
	ds_read_b128 v[226:229], v129 offset:22784
	v_max_i32_e32 v225, 0, v15
	v_fmac_f32_e32 v219, v225, v147
	s_waitcnt lgkmcnt(7)
; __device__ __forceinline__ void ph_indexer(const Params& p, char* shm) {
;     ...
;           IDX_TILE(ktp * 2, pr0);
;           __builtin_amdgcn_sched_barrier(0);
;           IDX_TILE(ktp * 2 + 1, pr1);
;           __builtin_amdgcn_sched_barrier(0);
;     ...
; #pragma unroll
;           for (int q = 0; q < 2; ++q) {
;             const float mine = half ? pr1[q] : pr0[q];
;             const float send = half ? pr0[q] : pr1[q];
;             const float recv = __shfl_xor(send, 32);
;             p.SC[(rowb + wid * 2 + q) * L + st * 128 + ktp * 64 + lane] = mine + recv;
;           }
	v_mfma_f32_16x16x32_bf16 v[0:3], v[74:77], v[172:175], 0
	v_mfma_f32_16x16x32_bf16 v[8:11], v[62:65], v[172:175], 0
	s_waitcnt lgkmcnt(6)
	v_mfma_f32_16x16x32_bf16 v[4:7], v[74:77], v[176:179], 0
	v_mfma_f32_16x16x32_bf16 v[12:15], v[62:65], v[176:179], 0
	v_max_i32_e32 v230, 0, v16
	v_fma_f32 v220, v230, v148, 0
	s_waitcnt lgkmcnt(5)
	v_mfma_f32_16x16x32_bf16 v[0:3], v[50:53], v[180:183], v[0:3]
	v_max_i32_e32 v231, 0, v17
	v_fmac_f32_e32 v220, v231, v149
	v_mfma_f32_16x16x32_bf16 v[8:11], v[66:69], v[180:183], v[8:11]
	v_max_i32_e32 v230, 0, v18
	v_fmac_f32_e32 v220, v230, v150
	s_waitcnt lgkmcnt(4)
	v_mfma_f32_16x16x32_bf16 v[4:7], v[50:53], v[184:187], v[4:7]
	v_max_i32_e32 v231, 0, v19
	v_fmac_f32_e32 v220, v231, v151
	v_mfma_f32_16x16x32_bf16 v[12:15], v[66:69], v[184:187], v[12:15]
	v_max_i32_e32 v230, 0, v24
	v_fmac_f32_e32 v220, v230, v152
	s_waitcnt lgkmcnt(3)
	v_mfma_f32_16x16x32_bf16 v[0:3], v[54:57], v[188:191], v[0:3]
	v_max_i32_e32 v231, 0, v25
	v_fmac_f32_e32 v220, v231, v153
	v_mfma_f32_16x16x32_bf16 v[8:11], v[70:73], v[188:191], v[8:11]
	v_max_i32_e32 v230, 0, v26
	v_fmac_f32_e32 v220, v230, v154
	v_max_i32_e32 v231, 0, v27
	s_waitcnt lgkmcnt(2)
	v_mfma_f32_16x16x32_bf16 v[4:7], v[54:57], v[192:195], v[4:7]
	v_fmac_f32_e32 v220, v231, v155
	v_max_i32_e32 v230, 0, v20
	v_fma_f32 v221, v230, v148, 0
	v_mfma_f32_16x16x32_bf16 v[12:15], v[70:73], v[192:195], v[12:15]
	v_max_i32_e32 v231, 0, v21
	v_fmac_f32_e32 v221, v231, v149
	v_max_i32_e32 v230, 0, v22
	s_waitcnt lgkmcnt(1)
	v_mfma_f32_16x16x32_bf16 v[0:3], v[58:61], v[196:199], v[0:3]
	v_fmac_f32_e32 v221, v230, v150
	v_max_i32_e32 v231, 0, v23
	v_fmac_f32_e32 v221, v231, v151
	v_mfma_f32_16x16x32_bf16 v[8:11], v[78:81], v[196:199], v[8:11]
	v_max_i32_e32 v230, 0, v28
	v_fmac_f32_e32 v221, v230, v152
	v_max_i32_e32 v231, 0, v29
	s_waitcnt lgkmcnt(0)
	v_mfma_f32_16x16x32_bf16 v[4:7], v[58:61], v[226:229], v[4:7]
	v_fmac_f32_e32 v221, v231, v153
	v_max_i32_e32 v230, 0, v30
	v_fmac_f32_e32 v221, v230, v154
	v_mfma_f32_16x16x32_bf16 v[12:15], v[78:81], v[226:229], v[12:15]
	v_max_i32_e32 v231, 0, v31
	v_fmac_f32_e32 v221, v231, v155
	v_mfma_f32_16x16x32_bf16 v[16:19], v[106:109], v[172:175], 0
	s_nop 1
	v_permlane16_swap_b32_e32 v200, v201
	v_permlane16_swap_b32_e32 v218, v219
	v_permlane16_swap_b32_e32 v202, v203
	v_mfma_f32_16x16x32_bf16 v[24:27], v[94:97], v[172:175], 0
	ds_read_b128 v[172:175], v129 offset:24576
	v_permlane16_swap_b32_e32 v220, v221
	v_add_f32_e32 v200, v200, v201
	v_add_f32_e32 v218, v218, v219
	v_add_f32_e32 v202, v202, v203
	v_mfma_f32_16x16x32_bf16 v[20:23], v[106:109], v[176:179], 0
	v_add_f32_e32 v220, v220, v221
	s_nop 1
	v_permlane32_swap_b32_e32 v200, v218
	v_permlane32_swap_b32_e32 v202, v220
	v_mfma_f32_16x16x32_bf16 v[28:31], v[94:97], v[176:179], 0
	ds_read_b128 v[176:179], v129 offset:24832
	v_add_f32_e32 v200, v200, v218
	v_add_f32_e32 v202, v202, v220
	global_store_dword v[232:233], v200, off nt
	global_store_dword v[234:235], v202, off nt
	v_mfma_f32_16x16x32_bf16 v[16:19], v[82:85], v[180:183], v[16:19]
	v_max_i32_e32 v224, 0, v0
	v_fma_f32 v222, v224, v140, 0
	v_mfma_f32_16x16x32_bf16 v[24:27], v[98:101], v[180:183], v[24:27]
	ds_read_b128 v[180:183], v129 offset:26624
	v_max_i32_e32 v225, 0, v1
	v_fmac_f32_e32 v222, v225, v141
	v_mfma_f32_16x16x32_bf16 v[20:23], v[82:85], v[184:187], v[20:23]
	v_max_i32_e32 v224, 0, v2
	v_fmac_f32_e32 v222, v224, v142
	v_max_i32_e32 v225, 0, v3
	v_mfma_f32_16x16x32_bf16 v[28:31], v[98:101], v[184:187], v[28:31]
	ds_read_b128 v[184:187], v129 offset:26880
	v_fmac_f32_e32 v222, v225, v143
	v_max_i32_e32 v224, 0, v8
	v_fmac_f32_e32 v222, v224, v144
	v_mfma_f32_16x16x32_bf16 v[16:19], v[86:89], v[188:191], v[16:19]
	v_max_i32_e32 v225, 0, v9
	v_fmac_f32_e32 v222, v225, v145
	v_max_i32_e32 v224, 0, v10
	v_mfma_f32_16x16x32_bf16 v[24:27], v[102:105], v[188:191], v[24:27]
	ds_read_b128 v[188:191], v129 offset:28672
	v_fmac_f32_e32 v222, v224, v146
	v_max_i32_e32 v225, 0, v11
	v_fmac_f32_e32 v222, v225, v147
	v_mfma_f32_16x16x32_bf16 v[20:23], v[86:89], v[192:195], v[20:23]
	v_max_i32_e32 v224, 0, v4
	v_fma_f32 v223, v224, v140, 0
	v_max_i32_e32 v225, 0, v5
	v_mfma_f32_16x16x32_bf16 v[28:31], v[102:105], v[192:195], v[28:31]
	ds_read_b128 v[192:195], v129 offset:28928
	v_fmac_f32_e32 v223, v225, v141
	v_max_i32_e32 v224, 0, v6
	v_fmac_f32_e32 v223, v224, v142
	v_mfma_f32_16x16x32_bf16 v[16:19], v[90:93], v[196:199], v[16:19]
	v_max_i32_e32 v225, 0, v7
	v_fmac_f32_e32 v223, v225, v143
	v_max_i32_e32 v224, 0, v12
	v_mfma_f32_16x16x32_bf16 v[24:27], v[110:113], v[196:199], v[24:27]
	ds_read_b128 v[196:199], v129 offset:30720
	v_fmac_f32_e32 v223, v224, v144
	v_max_i32_e32 v225, 0, v13
	v_fmac_f32_e32 v223, v225, v145
	v_mfma_f32_16x16x32_bf16 v[20:23], v[90:93], v[226:229], v[20:23]
	v_max_i32_e32 v224, 0, v14
	v_fmac_f32_e32 v223, v224, v146
	v_mfma_f32_16x16x32_bf16 v[28:31], v[110:113], v[226:229], v[28:31]
	ds_read_b128 v[226:229], v129 offset:30976
	v_max_i32_e32 v225, 0, v15
	v_fmac_f32_e32 v223, v225, v147
	s_waitcnt lgkmcnt(7)
	v_mfma_f32_16x16x32_bf16 v[0:3], v[74:77], v[172:175], 0
	v_mfma_f32_16x16x32_bf16 v[8:11], v[62:65], v[172:175], 0
	s_waitcnt lgkmcnt(6)
	v_mfma_f32_16x16x32_bf16 v[4:7], v[74:77], v[176:179], 0
	v_mfma_f32_16x16x32_bf16 v[12:15], v[62:65], v[176:179], 0
	v_max_i32_e32 v230, 0, v16
	v_fma_f32 v202, v230, v148, 0
	s_waitcnt lgkmcnt(5)
; __device__ __forceinline__ void ph_indexer(const Params& p, char* shm) {
;     ...
;           IDX_TILE(ktp * 2, pr0);
;           __builtin_amdgcn_sched_barrier(0);
;           IDX_TILE(ktp * 2 + 1, pr1);
;           __builtin_amdgcn_sched_barrier(0);
;     ...
; #pragma unroll
;           for (int q = 0; q < 2; ++q) {
;             const float mine = half ? pr1[q] : pr0[q];
;             const float send = half ? pr0[q] : pr1[q];
;             const float recv = __shfl_xor(send, 32);
;             p.SC[(rowb + wid * 2 + q) * L + st * 128 + ktp * 64 + lane] = mine + recv;
;           }
	v_mfma_f32_16x16x32_bf16 v[0:3], v[50:53], v[180:183], v[0:3]
	v_max_i32_e32 v231, 0, v17
	v_fmac_f32_e32 v202, v231, v149
	v_mfma_f32_16x16x32_bf16 v[8:11], v[66:69], v[180:183], v[8:11]
	v_max_i32_e32 v230, 0, v18
	v_fmac_f32_e32 v202, v230, v150
	s_waitcnt lgkmcnt(4)
	v_mfma_f32_16x16x32_bf16 v[4:7], v[50:53], v[184:187], v[4:7]
	v_max_i32_e32 v231, 0, v19
	v_fmac_f32_e32 v202, v231, v151
	v_mfma_f32_16x16x32_bf16 v[12:15], v[66:69], v[184:187], v[12:15]
	v_max_i32_e32 v230, 0, v24
	v_fmac_f32_e32 v202, v230, v152
	s_waitcnt lgkmcnt(3)
	v_mfma_f32_16x16x32_bf16 v[0:3], v[54:57], v[188:191], v[0:3]
	v_max_i32_e32 v231, 0, v25
	v_fmac_f32_e32 v202, v231, v153
	v_mfma_f32_16x16x32_bf16 v[8:11], v[70:73], v[188:191], v[8:11]
	v_max_i32_e32 v230, 0, v26
	v_fmac_f32_e32 v202, v230, v154
	v_max_i32_e32 v231, 0, v27
	s_waitcnt lgkmcnt(2)
	v_mfma_f32_16x16x32_bf16 v[4:7], v[54:57], v[192:195], v[4:7]
	v_fmac_f32_e32 v202, v231, v155
	v_max_i32_e32 v230, 0, v20
	v_fma_f32 v203, v230, v148, 0
	v_mfma_f32_16x16x32_bf16 v[12:15], v[70:73], v[192:195], v[12:15]
	v_max_i32_e32 v231, 0, v21
	v_fmac_f32_e32 v203, v231, v149
	v_max_i32_e32 v230, 0, v22
	s_waitcnt lgkmcnt(1)
	v_mfma_f32_16x16x32_bf16 v[0:3], v[58:61], v[196:199], v[0:3]
	v_fmac_f32_e32 v203, v230, v150
	v_max_i32_e32 v231, 0, v23
	v_fmac_f32_e32 v203, v231, v151
	v_mfma_f32_16x16x32_bf16 v[8:11], v[78:81], v[196:199], v[8:11]
	v_max_i32_e32 v230, 0, v28
	v_fmac_f32_e32 v203, v230, v152
	v_max_i32_e32 v231, 0, v29
	s_waitcnt lgkmcnt(0)
	v_mfma_f32_16x16x32_bf16 v[4:7], v[58:61], v[226:229], v[4:7]
	v_fmac_f32_e32 v203, v231, v153
	v_max_i32_e32 v230, 0, v30
	v_fmac_f32_e32 v203, v230, v154
	v_mfma_f32_16x16x32_bf16 v[12:15], v[78:81], v[226:229], v[12:15]
	v_max_i32_e32 v231, 0, v31
	v_fmac_f32_e32 v203, v231, v155
	v_mfma_f32_16x16x32_bf16 v[16:19], v[106:109], v[172:175], 0
	v_mfma_f32_16x16x32_bf16 v[24:27], v[94:97], v[172:175], 0
	v_mfma_f32_16x16x32_bf16 v[20:23], v[106:109], v[176:179], 0
	v_mfma_f32_16x16x32_bf16 v[28:31], v[94:97], v[176:179], 0
	v_mfma_f32_16x16x32_bf16 v[16:19], v[82:85], v[180:183], v[16:19]
	v_max_i32_e32 v224, 0, v0
	v_fma_f32 v218, v224, v140, 0
	v_mfma_f32_16x16x32_bf16 v[24:27], v[98:101], v[180:183], v[24:27]
	v_max_i32_e32 v225, 0, v1
	v_fmac_f32_e32 v218, v225, v141
	v_mfma_f32_16x16x32_bf16 v[20:23], v[82:85], v[184:187], v[20:23]
	v_max_i32_e32 v224, 0, v2
	v_fmac_f32_e32 v218, v224, v142
	v_max_i32_e32 v225, 0, v3
	v_mfma_f32_16x16x32_bf16 v[28:31], v[98:101], v[184:187], v[28:31]
	v_fmac_f32_e32 v218, v225, v143
	v_max_i32_e32 v224, 0, v8
	v_fmac_f32_e32 v218, v224, v144
	v_mfma_f32_16x16x32_bf16 v[16:19], v[86:89], v[188:191], v[16:19]
	v_max_i32_e32 v225, 0, v9
	v_fmac_f32_e32 v218, v225, v145
	v_max_i32_e32 v224, 0, v10
	v_mfma_f32_16x16x32_bf16 v[24:27], v[102:105], v[188:191], v[24:27]
	v_fmac_f32_e32 v218, v224, v146
	v_max_i32_e32 v225, 0, v11
	v_fmac_f32_e32 v218, v225, v147
	v_mfma_f32_16x16x32_bf16 v[20:23], v[86:89], v[192:195], v[20:23]
	v_max_i32_e32 v224, 0, v4
	v_fma_f32 v219, v224, v140, 0
	v_max_i32_e32 v225, 0, v5
	v_mfma_f32_16x16x32_bf16 v[28:31], v[102:105], v[192:195], v[28:31]
	v_fmac_f32_e32 v219, v225, v141
	v_max_i32_e32 v224, 0, v6
	v_fmac_f32_e32 v219, v224, v142
	v_mfma_f32_16x16x32_bf16 v[16:19], v[90:93], v[196:199], v[16:19]
	v_max_i32_e32 v225, 0, v7
	v_fmac_f32_e32 v219, v225, v143
	v_max_i32_e32 v224, 0, v12
	v_mfma_f32_16x16x32_bf16 v[24:27], v[110:113], v[196:199], v[24:27]
	v_fmac_f32_e32 v219, v224, v144
	v_max_i32_e32 v225, 0, v13
	v_fmac_f32_e32 v219, v225, v145
	v_mfma_f32_16x16x32_bf16 v[20:23], v[90:93], v[226:229], v[20:23]
	v_max_i32_e32 v224, 0, v14
	v_fmac_f32_e32 v219, v224, v146
	v_mfma_f32_16x16x32_bf16 v[28:31], v[110:113], v[226:229], v[28:31]
	v_max_i32_e32 v225, 0, v15
	v_fmac_f32_e32 v219, v225, v147
	s_cmp_lg_u32 s22, s44
	s_cbranch_scc0 .Lidx_flush_s0
	s_mov_b32 s4, s22
	s_branch .LBB0_920
.Lidx_flush_s0:
	s_nop 7
	v_max_i32_e32 v230, 0, v16
	v_fma_f32 v220, v230, v148, 0
	v_max_i32_e32 v231, 0, v17
	v_fmac_f32_e32 v220, v231, v149
	v_max_i32_e32 v230, 0, v18
	v_fmac_f32_e32 v220, v230, v150
	v_max_i32_e32 v231, 0, v19
	v_fmac_f32_e32 v220, v231, v151
	v_max_i32_e32 v230, 0, v24
	v_fmac_f32_e32 v220, v230, v152
	v_max_i32_e32 v231, 0, v25
	v_fmac_f32_e32 v220, v231, v153
	v_max_i32_e32 v230, 0, v26
	v_fmac_f32_e32 v220, v230, v154
	v_max_i32_e32 v231, 0, v27
	v_fmac_f32_e32 v220, v231, v155
	v_max_i32_e32 v230, 0, v20
	v_fma_f32 v221, v230, v148, 0
	v_max_i32_e32 v231, 0, v21
	v_fmac_f32_e32 v221, v231, v149
	v_max_i32_e32 v230, 0, v22
	v_fmac_f32_e32 v221, v230, v150
	v_max_i32_e32 v231, 0, v23
	v_fmac_f32_e32 v221, v231, v151
	v_max_i32_e32 v230, 0, v28
	v_fmac_f32_e32 v221, v230, v152
	v_max_i32_e32 v231, 0, v29
	v_fmac_f32_e32 v221, v231, v153
	v_max_i32_e32 v230, 0, v30
	v_fmac_f32_e32 v221, v230, v154
	v_max_i32_e32 v231, 0, v31
	v_fmac_f32_e32 v221, v231, v155
	s_nop 1
	v_permlane16_swap_b32_e32 v222, v223
	v_permlane16_swap_b32_e32 v218, v219
	v_permlane16_swap_b32_e32 v202, v203
	v_permlane16_swap_b32_e32 v220, v221
	v_add_f32_e32 v222, v222, v223
	v_add_f32_e32 v218, v218, v219
	v_add_f32_e32 v202, v202, v203
	v_add_f32_e32 v220, v220, v221
	s_nop 1
	v_permlane32_swap_b32_e32 v222, v218
	v_permlane32_swap_b32_e32 v202, v220
	v_add_f32_e32 v222, v222, v218
	v_add_f32_e32 v202, v202, v220
	global_store_dword v[232:233], v222, off offset:256 nt
	global_store_dword v[234:235], v202, off offset:256 nt

; __device__ __forceinline__ void ph_indexer(const Params& p, char* shm) {
;     ...
;           IDX_TILE(ktp * 2, pr0);
;           __builtin_amdgcn_sched_barrier(0);
;           IDX_TILE(ktp * 2 + 1, pr1);
;           __builtin_amdgcn_sched_barrier(0);
;     ...
; #pragma unroll
;           for (int q = 0; q < 2; ++q) {
;             const float mine = half ? pr1[q] : pr0[q];
;             const float send = half ? pr0[q] : pr1[q];
;             const float recv = __shfl_xor(send, 32);
;             p.SC[(rowb + wid * 2 + q) * L + st * 128 + ktp * 64 + lane] = mine + recv;
;           }
.LBB0_943:
	s_lshl_b32 s3, s4, 15
	s_and_b32 s3, s3, 0x8000
	s_lshl_b32 s4, s4, 7
	v_or_b32_e32 v112, s3, v117
	v_lshl_add_u64 v[110:111], s[4:5], 2, v[124:125]
	ds_read_b128 v[160:163], v112
	ds_read_b128 v[164:167], v112 offset:256
	ds_read_b128 v[168:171], v112 offset:2048
	ds_read_b128 v[172:175], v112 offset:2304
	ds_read_b128 v[176:179], v112 offset:4096
	ds_read_b128 v[106:109], v112 offset:4352
	ds_read_b128 v[102:105], v112 offset:6144
	ds_read_b128 v[98:101], v112 offset:6400
	s_waitcnt lgkmcnt(8)
	v_cvt_f32_f16_e32 v128, v34
	v_cvt_f32_f16_sdwa v129, v34 dst_sel:DWORD dst_unused:UNUSED_PAD src0_sel:WORD_1
	v_cvt_f32_f16_e32 v130, v35
	v_cvt_f32_f16_sdwa v131, v35 dst_sel:DWORD dst_unused:UNUSED_PAD src0_sel:WORD_1
	v_cvt_f32_f16_e32 v132, v36
	v_cvt_f32_f16_sdwa v133, v36 dst_sel:DWORD dst_unused:UNUSED_PAD src0_sel:WORD_1
	v_cvt_f32_f16_e32 v134, v37
	v_cvt_f32_f16_sdwa v135, v37 dst_sel:DWORD dst_unused:UNUSED_PAD src0_sel:WORD_1
	v_cvt_f32_f16_e32 v136, v38
	v_cvt_f32_f16_sdwa v137, v38 dst_sel:DWORD dst_unused:UNUSED_PAD src0_sel:WORD_1
	v_cvt_f32_f16_e32 v138, v39
	v_cvt_f32_f16_sdwa v139, v39 dst_sel:DWORD dst_unused:UNUSED_PAD src0_sel:WORD_1
	v_cvt_f32_f16_e32 v140, v40
	v_cvt_f32_f16_sdwa v141, v40 dst_sel:DWORD dst_unused:UNUSED_PAD src0_sel:WORD_1
	v_cvt_f32_f16_e32 v142, v41
	v_cvt_f32_f16_sdwa v143, v41 dst_sel:DWORD dst_unused:UNUSED_PAD src0_sel:WORD_1
	s_cmp_eq_u32 s20, 1
	s_cbranch_scc1 .Lidx_first_s1
	s_waitcnt lgkmcnt(7)
	v_mfma_f32_16x16x32_bf16 v[0:3], v[58:61], v[160:163], 0
	v_max_i32_e32 v226, 0, v184
	v_fma_f32 v220, v226, v136, 0
	v_max_i32_e32 v227, 0, v185
	v_mfma_f32_16x16x32_bf16 v[8:11], v[28:31], v[160:163], 0
	v_fmac_f32_e32 v220, v227, v137
	v_max_i32_e32 v226, 0, v186
	v_fmac_f32_e32 v220, v226, v138
	s_waitcnt lgkmcnt(6)
	v_mfma_f32_16x16x32_bf16 v[4:7], v[58:61], v[164:167], 0
	v_max_i32_e32 v227, 0, v187
	v_fmac_f32_e32 v220, v227, v139
	v_max_i32_e32 v226, 0, v192
	v_mfma_f32_16x16x32_bf16 v[12:15], v[28:31], v[164:167], 0
	v_fmac_f32_e32 v220, v226, v140
	v_max_i32_e32 v227, 0, v193
	v_fmac_f32_e32 v220, v227, v141
	s_waitcnt lgkmcnt(5)
	v_mfma_f32_16x16x32_bf16 v[0:3], v[16:19], v[168:171], v[0:3]
	v_max_i32_e32 v226, 0, v194
	v_fmac_f32_e32 v220, v226, v142
	v_max_i32_e32 v227, 0, v195
	v_mfma_f32_16x16x32_bf16 v[8:11], v[50:53], v[168:171], v[8:11]
	v_fmac_f32_e32 v220, v227, v143
	v_max_i32_e32 v226, 0, v188
	v_fma_f32 v221, v226, v136, 0
	s_waitcnt lgkmcnt(4)
	v_mfma_f32_16x16x32_bf16 v[4:7], v[16:19], v[172:175], v[4:7]
	v_max_i32_e32 v227, 0, v189
	v_fmac_f32_e32 v221, v227, v137
	v_max_i32_e32 v226, 0, v190
	v_mfma_f32_16x16x32_bf16 v[12:15], v[50:53], v[172:175], v[12:15]
	v_fmac_f32_e32 v221, v226, v138
	v_max_i32_e32 v227, 0, v191
	v_fmac_f32_e32 v221, v227, v139
	s_waitcnt lgkmcnt(3)
	v_mfma_f32_16x16x32_bf16 v[0:3], v[20:23], v[176:179], v[0:3]
	v_max_i32_e32 v226, 0, v196
	v_fmac_f32_e32 v221, v226, v140
	v_max_i32_e32 v227, 0, v197
	v_mfma_f32_16x16x32_bf16 v[8:11], v[54:57], v[176:179], v[8:11]
	v_fmac_f32_e32 v221, v227, v141
	v_max_i32_e32 v226, 0, v198
	v_fmac_f32_e32 v221, v226, v142
	s_waitcnt lgkmcnt(2)
	v_mfma_f32_16x16x32_bf16 v[4:7], v[20:23], v[106:109], v[4:7]
	v_max_i32_e32 v227, 0, v199
	v_fmac_f32_e32 v221, v227, v143
	s_nop 1
	v_mfma_f32_16x16x32_bf16 v[12:15], v[54:57], v[106:109], v[12:15]
	v_permlane16_swap_b32_e32 v222, v223
	v_permlane16_swap_b32_e32 v218, v219
	v_permlane16_swap_b32_e32 v202, v203
	s_waitcnt lgkmcnt(1)
	v_mfma_f32_16x16x32_bf16 v[0:3], v[24:27], v[102:105], v[0:3]
	v_permlane16_swap_b32_e32 v220, v221
	v_add_f32_e32 v222, v222, v223
	v_add_f32_e32 v218, v218, v219
	v_mfma_f32_16x16x32_bf16 v[8:11], v[62:65], v[102:105], v[8:11]
	v_add_f32_e32 v202, v202, v203
	v_add_f32_e32 v220, v220, v221
	s_nop 1
	s_waitcnt lgkmcnt(0)
	v_mfma_f32_16x16x32_bf16 v[4:7], v[24:27], v[98:101], v[4:7]
	v_permlane32_swap_b32_e32 v222, v218
	v_permlane32_swap_b32_e32 v202, v220
	v_add_f32_e32 v222, v222, v218
	v_mfma_f32_16x16x32_bf16 v[12:15], v[62:65], v[98:101], v[12:15]
	v_add_f32_e32 v202, v202, v220
	global_store_dword v[228:229], v222, off offset:256 nt
	global_store_dword v[230:231], v202, off offset:256 nt
	s_branch .Lidx_join_s1

; __device__ __forceinline__ void ph_indexer(const Params& p, char* shm) {
;     ...
;           IDX_TILE(ktp * 2, pr0);
;           __builtin_amdgcn_sched_barrier(0);
;           IDX_TILE(ktp * 2 + 1, pr1);
;           __builtin_amdgcn_sched_barrier(0);
.Lidx_nostage_s1_3:
	v_max_i32_e32 v225, 0, v1
	v_fmac_f32_e32 v200, v225, v129
	v_mfma_f32_16x16x32_bf16 v[188:191], v[66:69], v[172:175], v[188:191]
	v_max_i32_e32 v224, 0, v2
	v_fmac_f32_e32 v200, v224, v130
	v_max_i32_e32 v225, 0, v3
	v_mfma_f32_16x16x32_bf16 v[196:199], v[82:85], v[172:175], v[196:199]
	ds_read_b128 v[172:175], v112 offset:10496
	v_fmac_f32_e32 v200, v225, v131
	v_max_i32_e32 v224, 0, v8
	v_fmac_f32_e32 v200, v224, v132
	v_mfma_f32_16x16x32_bf16 v[184:187], v[70:73], v[176:179], v[184:187]
	v_max_i32_e32 v225, 0, v9
	v_fmac_f32_e32 v200, v225, v133
	v_max_i32_e32 v224, 0, v10
	v_mfma_f32_16x16x32_bf16 v[192:195], v[86:89], v[176:179], v[192:195]
	ds_read_b128 v[176:179], v112 offset:12288
	v_fmac_f32_e32 v200, v224, v134
	v_max_i32_e32 v225, 0, v11
	v_fmac_f32_e32 v200, v225, v135
	v_mfma_f32_16x16x32_bf16 v[188:191], v[70:73], v[106:109], v[188:191]
	v_max_i32_e32 v224, 0, v4
	v_fma_f32 v201, v224, v128, 0
	v_max_i32_e32 v225, 0, v5
	v_mfma_f32_16x16x32_bf16 v[196:199], v[86:89], v[106:109], v[196:199]
	ds_read_b128 v[106:109], v112 offset:12544
	v_fmac_f32_e32 v201, v225, v129
	v_max_i32_e32 v224, 0, v6
	v_fmac_f32_e32 v201, v224, v130
	v_mfma_f32_16x16x32_bf16 v[184:187], v[74:77], v[102:105], v[184:187]
	v_max_i32_e32 v225, 0, v7
	v_fmac_f32_e32 v201, v225, v131
	v_max_i32_e32 v224, 0, v12
	v_mfma_f32_16x16x32_bf16 v[192:195], v[94:97], v[102:105], v[192:195]
	ds_read_b128 v[102:105], v112 offset:14336
	v_fmac_f32_e32 v201, v224, v132
	v_max_i32_e32 v225, 0, v13
	v_fmac_f32_e32 v201, v225, v133
	v_mfma_f32_16x16x32_bf16 v[188:191], v[74:77], v[98:101], v[188:191]
	v_max_i32_e32 v224, 0, v14
	v_fmac_f32_e32 v201, v224, v134
	v_mfma_f32_16x16x32_bf16 v[196:199], v[94:97], v[98:101], v[196:199]
	ds_read_b128 v[98:101], v112 offset:14592
	v_max_i32_e32 v225, 0, v15
	v_fmac_f32_e32 v201, v225, v135
	s_waitcnt lgkmcnt(7)
	v_mfma_f32_16x16x32_bf16 v[0:3], v[58:61], v[160:163], 0
	v_mfma_f32_16x16x32_bf16 v[8:11], v[28:31], v[160:163], 0
	s_waitcnt lgkmcnt(6)
	v_mfma_f32_16x16x32_bf16 v[4:7], v[58:61], v[164:167], 0
	v_mfma_f32_16x16x32_bf16 v[12:15], v[28:31], v[164:167], 0
	v_max_i32_e32 v226, 0, v184
	v_fma_f32 v202, v226, v136, 0
	s_waitcnt lgkmcnt(5)
	v_mfma_f32_16x16x32_bf16 v[0:3], v[16:19], v[168:171], v[0:3]
	v_max_i32_e32 v227, 0, v185
	v_fmac_f32_e32 v202, v227, v137
	v_mfma_f32_16x16x32_bf16 v[8:11], v[50:53], v[168:171], v[8:11]
	v_max_i32_e32 v226, 0, v186
	v_fmac_f32_e32 v202, v226, v138
	s_waitcnt lgkmcnt(4)
	v_mfma_f32_16x16x32_bf16 v[4:7], v[16:19], v[172:175], v[4:7]
	v_max_i32_e32 v227, 0, v187
	v_fmac_f32_e32 v202, v227, v139
	v_mfma_f32_16x16x32_bf16 v[12:15], v[50:53], v[172:175], v[12:15]
	v_max_i32_e32 v226, 0, v192
	v_fmac_f32_e32 v202, v226, v140
	s_waitcnt lgkmcnt(3)
	v_mfma_f32_16x16x32_bf16 v[0:3], v[20:23], v[176:179], v[0:3]
	v_max_i32_e32 v227, 0, v193
	v_fmac_f32_e32 v202, v227, v141
	v_mfma_f32_16x16x32_bf16 v[8:11], v[54:57], v[176:179], v[8:11]
	v_max_i32_e32 v226, 0, v194
	v_fmac_f32_e32 v202, v226, v142
	v_max_i32_e32 v227, 0, v195
	s_waitcnt lgkmcnt(2)
	v_mfma_f32_16x16x32_bf16 v[4:7], v[20:23], v[106:109], v[4:7]
	v_fmac_f32_e32 v202, v227, v143
	v_max_i32_e32 v226, 0, v188
	v_fma_f32 v203, v226, v136, 0
	v_mfma_f32_16x16x32_bf16 v[12:15], v[54:57], v[106:109], v[12:15]
	v_max_i32_e32 v227, 0, v189
	v_fmac_f32_e32 v203, v227, v137
	v_max_i32_e32 v226, 0, v190
	s_waitcnt lgkmcnt(1)
	v_mfma_f32_16x16x32_bf16 v[0:3], v[24:27], v[102:105], v[0:3]
	v_fmac_f32_e32 v203, v226, v138
	v_max_i32_e32 v227, 0, v191
	v_fmac_f32_e32 v203, v227, v139
	v_mfma_f32_16x16x32_bf16 v[8:11], v[62:65], v[102:105], v[8:11]
	v_max_i32_e32 v226, 0, v196
	v_fmac_f32_e32 v203, v226, v140
	v_max_i32_e32 v227, 0, v197
	s_waitcnt lgkmcnt(0)
	v_mfma_f32_16x16x32_bf16 v[4:7], v[24:27], v[98:101], v[4:7]
	v_fmac_f32_e32 v203, v227, v141
	v_max_i32_e32 v226, 0, v198
	v_fmac_f32_e32 v203, v226, v142
	v_mfma_f32_16x16x32_bf16 v[12:15], v[62:65], v[98:101], v[12:15]
	v_max_i32_e32 v227, 0, v199
	v_fmac_f32_e32 v203, v227, v143
	v_mfma_f32_16x16x32_bf16 v[184:187], v[90:93], v[160:163], 0
	v_mfma_f32_16x16x32_bf16 v[192:195], v[78:81], v[160:163], 0
	ds_read_b128 v[160:163], v112 offset:16384
	v_mfma_f32_16x16x32_bf16 v[188:191], v[90:93], v[164:167], 0
	v_mfma_f32_16x16x32_bf16 v[196:199], v[78:81], v[164:167], 0
	ds_read_b128 v[164:167], v112 offset:16640
	v_mfma_f32_16x16x32_bf16 v[184:187], v[66:69], v[168:171], v[184:187]
	v_max_i32_e32 v224, 0, v0
	v_fma_f32 v218, v224, v128, 0
	v_mfma_f32_16x16x32_bf16 v[192:195], v[82:85], v[168:171], v[192:195]
	ds_read_b128 v[168:171], v112 offset:18432
	v_max_i32_e32 v225, 0, v1
	v_fmac_f32_e32 v218, v225, v129
	v_mfma_f32_16x16x32_bf16 v[188:191], v[66:69], v[172:175], v[188:191]
	v_max_i32_e32 v224, 0, v2
	v_fmac_f32_e32 v218, v224, v130
	v_max_i32_e32 v225, 0, v3
	v_mfma_f32_16x16x32_bf16 v[196:199], v[82:85], v[172:175], v[196:199]
	ds_read_b128 v[172:175], v112 offset:18688
	v_fmac_f32_e32 v218, v225, v131
	v_max_i32_e32 v224, 0, v8
	v_fmac_f32_e32 v218, v224, v132
	v_mfma_f32_16x16x32_bf16 v[184:187], v[70:73], v[176:179], v[184:187]
	v_max_i32_e32 v225, 0, v9
	v_fmac_f32_e32 v218, v225, v133
	v_max_i32_e32 v224, 0, v10
	v_mfma_f32_16x16x32_bf16 v[192:195], v[86:89], v[176:179], v[192:195]
	ds_read_b128 v[176:179], v112 offset:20480
	v_fmac_f32_e32 v218, v224, v134
	v_max_i32_e32 v225, 0, v11
	v_fmac_f32_e32 v218, v225, v135
	v_mfma_f32_16x16x32_bf16 v[188:191], v[70:73], v[106:109], v[188:191]
	v_max_i32_e32 v224, 0, v4
	v_fma_f32 v219, v224, v128, 0
	v_max_i32_e32 v225, 0, v5
	v_mfma_f32_16x16x32_bf16 v[196:199], v[86:89], v[106:109], v[196:199]
	ds_read_b128 v[106:109], v112 offset:20736
	v_fmac_f32_e32 v219, v225, v129
	v_max_i32_e32 v224, 0, v6
	v_fmac_f32_e32 v219, v224, v130
	v_mfma_f32_16x16x32_bf16 v[184:187], v[74:77], v[102:105], v[184:187]
	v_max_i32_e32 v225, 0, v7
	v_fmac_f32_e32 v219, v225, v131
	v_max_i32_e32 v224, 0, v12
	v_mfma_f32_16x16x32_bf16 v[192:195], v[94:97], v[102:105], v[192:195]
	ds_read_b128 v[102:105], v112 offset:22528
	v_fmac_f32_e32 v219, v224, v132
	v_max_i32_e32 v225, 0, v13
	v_fmac_f32_e32 v219, v225, v133
	v_mfma_f32_16x16x32_bf16 v[188:191], v[74:77], v[98:101], v[188:191]
	v_max_i32_e32 v224, 0, v14
	v_fmac_f32_e32 v219, v224, v134
	v_mfma_f32_16x16x32_bf16 v[196:199], v[94:97], v[98:101], v[196:199]
	ds_read_b128 v[98:101], v112 offset:22784
	v_max_i32_e32 v225, 0, v15
	v_fmac_f32_e32 v219, v225, v135
	s_waitcnt lgkmcnt(7)
; __device__ __forceinline__ void ph_indexer(const Params& p, char* shm) {
;     ...
;           IDX_TILE(ktp * 2, pr0);
;           __builtin_amdgcn_sched_barrier(0);
;           IDX_TILE(ktp * 2 + 1, pr1);
;           __builtin_amdgcn_sched_barrier(0);
;     ...
; #pragma unroll
;           for (int q = 0; q < 2; ++q) {
;             const float mine = half ? pr1[q] : pr0[q];
;             const float send = half ? pr0[q] : pr1[q];
;             const float recv = __shfl_xor(send, 32);
;             p.SC[(rowb + wid * 2 + q) * L + st * 128 + ktp * 64 + lane] = mine + recv;
;           }
	v_mfma_f32_16x16x32_bf16 v[0:3], v[58:61], v[160:163], 0
	v_mfma_f32_16x16x32_bf16 v[8:11], v[28:31], v[160:163], 0
	s_waitcnt lgkmcnt(6)
	v_mfma_f32_16x16x32_bf16 v[4:7], v[58:61], v[164:167], 0
	v_mfma_f32_16x16x32_bf16 v[12:15], v[28:31], v[164:167], 0
	v_max_i32_e32 v226, 0, v184
	v_fma_f32 v220, v226, v136, 0
	s_waitcnt lgkmcnt(5)
	v_mfma_f32_16x16x32_bf16 v[0:3], v[16:19], v[168:171], v[0:3]
	v_max_i32_e32 v227, 0, v185
	v_fmac_f32_e32 v220, v227, v137
	v_mfma_f32_16x16x32_bf16 v[8:11], v[50:53], v[168:171], v[8:11]
	v_max_i32_e32 v226, 0, v186
	v_fmac_f32_e32 v220, v226, v138
	s_waitcnt lgkmcnt(4)
	v_mfma_f32_16x16x32_bf16 v[4:7], v[16:19], v[172:175], v[4:7]
	v_max_i32_e32 v227, 0, v187
	v_fmac_f32_e32 v220, v227, v139
	v_mfma_f32_16x16x32_bf16 v[12:15], v[50:53], v[172:175], v[12:15]
	v_max_i32_e32 v226, 0, v192
	v_fmac_f32_e32 v220, v226, v140
	s_waitcnt lgkmcnt(3)
	v_mfma_f32_16x16x32_bf16 v[0:3], v[20:23], v[176:179], v[0:3]
	v_max_i32_e32 v227, 0, v193
	v_fmac_f32_e32 v220, v227, v141
	v_mfma_f32_16x16x32_bf16 v[8:11], v[54:57], v[176:179], v[8:11]
	v_max_i32_e32 v226, 0, v194
	v_fmac_f32_e32 v220, v226, v142
	v_max_i32_e32 v227, 0, v195
	s_waitcnt lgkmcnt(2)
	v_mfma_f32_16x16x32_bf16 v[4:7], v[20:23], v[106:109], v[4:7]
	v_fmac_f32_e32 v220, v227, v143
	v_max_i32_e32 v226, 0, v188
	v_fma_f32 v221, v226, v136, 0
	v_mfma_f32_16x16x32_bf16 v[12:15], v[54:57], v[106:109], v[12:15]
	v_max_i32_e32 v227, 0, v189
	v_fmac_f32_e32 v221, v227, v137
	v_max_i32_e32 v226, 0, v190
	s_waitcnt lgkmcnt(1)
	v_mfma_f32_16x16x32_bf16 v[0:3], v[24:27], v[102:105], v[0:3]
	v_fmac_f32_e32 v221, v226, v138
	v_max_i32_e32 v227, 0, v191
	v_fmac_f32_e32 v221, v227, v139
	v_mfma_f32_16x16x32_bf16 v[8:11], v[62:65], v[102:105], v[8:11]
	v_max_i32_e32 v226, 0, v196
	v_fmac_f32_e32 v221, v226, v140
	v_max_i32_e32 v227, 0, v197
	s_waitcnt lgkmcnt(0)
	v_mfma_f32_16x16x32_bf16 v[4:7], v[24:27], v[98:101], v[4:7]
	v_fmac_f32_e32 v221, v227, v141
	v_max_i32_e32 v226, 0, v198
	v_fmac_f32_e32 v221, v226, v142
	v_mfma_f32_16x16x32_bf16 v[12:15], v[62:65], v[98:101], v[12:15]
	v_max_i32_e32 v227, 0, v199
	v_fmac_f32_e32 v221, v227, v143
	v_mfma_f32_16x16x32_bf16 v[184:187], v[90:93], v[160:163], 0
	s_nop 1
	v_permlane16_swap_b32_e32 v200, v201
	v_permlane16_swap_b32_e32 v218, v219
	v_permlane16_swap_b32_e32 v202, v203
	v_mfma_f32_16x16x32_bf16 v[192:195], v[78:81], v[160:163], 0
	ds_read_b128 v[160:163], v112 offset:24576
	v_permlane16_swap_b32_e32 v220, v221
	v_add_f32_e32 v200, v200, v201
	v_add_f32_e32 v218, v218, v219
	v_add_f32_e32 v202, v202, v203
	v_mfma_f32_16x16x32_bf16 v[188:191], v[90:93], v[164:167], 0
	v_add_f32_e32 v220, v220, v221
	s_nop 1
	v_permlane32_swap_b32_e32 v200, v218
	v_permlane32_swap_b32_e32 v202, v220
	v_mfma_f32_16x16x32_bf16 v[196:199], v[78:81], v[164:167], 0
	ds_read_b128 v[164:167], v112 offset:24832
	v_add_f32_e32 v200, v200, v218
	v_add_f32_e32 v202, v202, v220
	global_store_dword v[228:229], v200, off nt
	global_store_dword v[230:231], v202, off nt
	v_mfma_f32_16x16x32_bf16 v[184:187], v[66:69], v[168:171], v[184:187]
	v_max_i32_e32 v224, 0, v0
	v_fma_f32 v222, v224, v128, 0
	v_mfma_f32_16x16x32_bf16 v[192:195], v[82:85], v[168:171], v[192:195]
	ds_read_b128 v[168:171], v112 offset:26624
	v_max_i32_e32 v225, 0, v1
	v_fmac_f32_e32 v222, v225, v129
	v_mfma_f32_16x16x32_bf16 v[188:191], v[66:69], v[172:175], v[188:191]
	v_max_i32_e32 v224, 0, v2
	v_fmac_f32_e32 v222, v224, v130
	v_max_i32_e32 v225, 0, v3
	v_mfma_f32_16x16x32_bf16 v[196:199], v[82:85], v[172:175], v[196:199]
	ds_read_b128 v[172:175], v112 offset:26880
	v_fmac_f32_e32 v222, v225, v131
	v_max_i32_e32 v224, 0, v8
	v_fmac_f32_e32 v222, v224, v132
	v_mfma_f32_16x16x32_bf16 v[184:187], v[70:73], v[176:179], v[184:187]
	v_max_i32_e32 v225, 0, v9
	v_fmac_f32_e32 v222, v225, v133
	v_max_i32_e32 v224, 0, v10
	v_mfma_f32_16x16x32_bf16 v[192:195], v[86:89], v[176:179], v[192:195]
	ds_read_b128 v[176:179], v112 offset:28672
	v_fmac_f32_e32 v222, v224, v134
	v_max_i32_e32 v225, 0, v11
	v_fmac_f32_e32 v222, v225, v135
	v_mfma_f32_16x16x32_bf16 v[188:191], v[70:73], v[106:109], v[188:191]
	v_max_i32_e32 v224, 0, v4
	v_fma_f32 v223, v224, v128, 0
	v_max_i32_e32 v225, 0, v5
	v_mfma_f32_16x16x32_bf16 v[196:199], v[86:89], v[106:109], v[196:199]
	ds_read_b128 v[106:109], v112 offset:28928
	v_fmac_f32_e32 v223, v225, v129
	v_max_i32_e32 v224, 0, v6
	v_fmac_f32_e32 v223, v224, v130
	v_mfma_f32_16x16x32_bf16 v[184:187], v[74:77], v[102:105], v[184:187]
	v_max_i32_e32 v225, 0, v7
	v_fmac_f32_e32 v223, v225, v131
	v_max_i32_e32 v224, 0, v12
	v_mfma_f32_16x16x32_bf16 v[192:195], v[94:97], v[102:105], v[192:195]
	ds_read_b128 v[102:105], v112 offset:30720
	v_fmac_f32_e32 v223, v224, v132
	v_max_i32_e32 v225, 0, v13
	v_fmac_f32_e32 v223, v225, v133
	v_mfma_f32_16x16x32_bf16 v[188:191], v[74:77], v[98:101], v[188:191]
	v_max_i32_e32 v224, 0, v14
	v_fmac_f32_e32 v223, v224, v134
	v_mfma_f32_16x16x32_bf16 v[196:199], v[94:97], v[98:101], v[196:199]
	ds_read_b128 v[98:101], v112 offset:30976
	v_max_i32_e32 v225, 0, v15
	v_fmac_f32_e32 v223, v225, v135
	s_waitcnt lgkmcnt(7)
	v_mfma_f32_16x16x32_bf16 v[0:3], v[58:61], v[160:163], 0
	v_mfma_f32_16x16x32_bf16 v[8:11], v[28:31], v[160:163], 0
	s_waitcnt lgkmcnt(6)
	v_mfma_f32_16x16x32_bf16 v[4:7], v[58:61], v[164:167], 0
	v_mfma_f32_16x16x32_bf16 v[12:15], v[28:31], v[164:167], 0
	v_max_i32_e32 v226, 0, v184
	v_fma_f32 v202, v226, v136, 0
	s_waitcnt lgkmcnt(5)
; __device__ __forceinline__ void ph_indexer(const Params& p, char* shm) {
;     ...
;           IDX_TILE(ktp * 2, pr0);
;           __builtin_amdgcn_sched_barrier(0);
;           IDX_TILE(ktp * 2 + 1, pr1);
;           __builtin_amdgcn_sched_barrier(0);
;     ...
; #pragma unroll
;           for (int q = 0; q < 2; ++q) {
;             const float mine = half ? pr1[q] : pr0[q];
;             const float send = half ? pr0[q] : pr1[q];
;             const float recv = __shfl_xor(send, 32);
;             p.SC[(rowb + wid * 2 + q) * L + st * 128 + ktp * 64 + lane] = mine + recv;
;           }
	v_mfma_f32_16x16x32_bf16 v[0:3], v[16:19], v[168:171], v[0:3]
	v_max_i32_e32 v227, 0, v185
	v_fmac_f32_e32 v202, v227, v137
	v_mfma_f32_16x16x32_bf16 v[8:11], v[50:53], v[168:171], v[8:11]
	v_max_i32_e32 v226, 0, v186
	v_fmac_f32_e32 v202, v226, v138
	s_waitcnt lgkmcnt(4)
	v_mfma_f32_16x16x32_bf16 v[4:7], v[16:19], v[172:175], v[4:7]
	v_max_i32_e32 v227, 0, v187
	v_fmac_f32_e32 v202, v227, v139
	v_mfma_f32_16x16x32_bf16 v[12:15], v[50:53], v[172:175], v[12:15]
	v_max_i32_e32 v226, 0, v192
	v_fmac_f32_e32 v202, v226, v140
	s_waitcnt lgkmcnt(3)
	v_mfma_f32_16x16x32_bf16 v[0:3], v[20:23], v[176:179], v[0:3]
	v_max_i32_e32 v227, 0, v193
	v_fmac_f32_e32 v202, v227, v141
	v_mfma_f32_16x16x32_bf16 v[8:11], v[54:57], v[176:179], v[8:11]
	v_max_i32_e32 v226, 0, v194
	v_fmac_f32_e32 v202, v226, v142
	v_max_i32_e32 v227, 0, v195
	s_waitcnt lgkmcnt(2)
	v_mfma_f32_16x16x32_bf16 v[4:7], v[20:23], v[106:109], v[4:7]
	v_fmac_f32_e32 v202, v227, v143
	v_max_i32_e32 v226, 0, v188
	v_fma_f32 v203, v226, v136, 0
	v_mfma_f32_16x16x32_bf16 v[12:15], v[54:57], v[106:109], v[12:15]
	v_max_i32_e32 v227, 0, v189
	v_fmac_f32_e32 v203, v227, v137
	v_max_i32_e32 v226, 0, v190
	s_waitcnt lgkmcnt(1)
	v_mfma_f32_16x16x32_bf16 v[0:3], v[24:27], v[102:105], v[0:3]
	v_fmac_f32_e32 v203, v226, v138
	v_max_i32_e32 v227, 0, v191
	v_fmac_f32_e32 v203, v227, v139
	v_mfma_f32_16x16x32_bf16 v[8:11], v[62:65], v[102:105], v[8:11]
	v_max_i32_e32 v226, 0, v196
	v_fmac_f32_e32 v203, v226, v140
	v_max_i32_e32 v227, 0, v197
	s_waitcnt lgkmcnt(0)
	v_mfma_f32_16x16x32_bf16 v[4:7], v[24:27], v[98:101], v[4:7]
	v_fmac_f32_e32 v203, v227, v141
	v_max_i32_e32 v226, 0, v198
	v_fmac_f32_e32 v203, v226, v142
	v_mfma_f32_16x16x32_bf16 v[12:15], v[62:65], v[98:101], v[12:15]
	v_max_i32_e32 v227, 0, v199
	v_fmac_f32_e32 v203, v227, v143
	v_mfma_f32_16x16x32_bf16 v[184:187], v[90:93], v[160:163], 0
	v_mfma_f32_16x16x32_bf16 v[192:195], v[78:81], v[160:163], 0
	v_mfma_f32_16x16x32_bf16 v[188:191], v[90:93], v[164:167], 0
	v_mfma_f32_16x16x32_bf16 v[196:199], v[78:81], v[164:167], 0
	v_mfma_f32_16x16x32_bf16 v[184:187], v[66:69], v[168:171], v[184:187]
	v_max_i32_e32 v224, 0, v0
	v_fma_f32 v218, v224, v128, 0
	v_mfma_f32_16x16x32_bf16 v[192:195], v[82:85], v[168:171], v[192:195]
	v_max_i32_e32 v225, 0, v1
	v_fmac_f32_e32 v218, v225, v129
	v_mfma_f32_16x16x32_bf16 v[188:191], v[66:69], v[172:175], v[188:191]
	v_max_i32_e32 v224, 0, v2
	v_fmac_f32_e32 v218, v224, v130
	v_max_i32_e32 v225, 0, v3
	v_mfma_f32_16x16x32_bf16 v[196:199], v[82:85], v[172:175], v[196:199]
	v_fmac_f32_e32 v218, v225, v131
	v_max_i32_e32 v224, 0, v8
	v_fmac_f32_e32 v218, v224, v132
	v_mfma_f32_16x16x32_bf16 v[184:187], v[70:73], v[176:179], v[184:187]
	v_max_i32_e32 v225, 0, v9
	v_fmac_f32_e32 v218, v225, v133
	v_max_i32_e32 v224, 0, v10
	v_mfma_f32_16x16x32_bf16 v[192:195], v[86:89], v[176:179], v[192:195]
	v_fmac_f32_e32 v218, v224, v134
	v_max_i32_e32 v225, 0, v11
	v_fmac_f32_e32 v218, v225, v135
	v_mfma_f32_16x16x32_bf16 v[188:191], v[70:73], v[106:109], v[188:191]
	v_max_i32_e32 v224, 0, v4
	v_fma_f32 v219, v224, v128, 0
	v_max_i32_e32 v225, 0, v5
	v_mfma_f32_16x16x32_bf16 v[196:199], v[86:89], v[106:109], v[196:199]
	v_fmac_f32_e32 v219, v225, v129
	v_max_i32_e32 v224, 0, v6
	v_fmac_f32_e32 v219, v224, v130
	v_mfma_f32_16x16x32_bf16 v[184:187], v[74:77], v[102:105], v[184:187]
	v_max_i32_e32 v225, 0, v7
	v_fmac_f32_e32 v219, v225, v131
	v_max_i32_e32 v224, 0, v12
	v_mfma_f32_16x16x32_bf16 v[192:195], v[94:97], v[102:105], v[192:195]
	v_fmac_f32_e32 v219, v224, v132
	v_max_i32_e32 v225, 0, v13
	v_fmac_f32_e32 v219, v225, v133
	v_mfma_f32_16x16x32_bf16 v[188:191], v[74:77], v[98:101], v[188:191]
	v_max_i32_e32 v224, 0, v14
	v_fmac_f32_e32 v219, v224, v134
	v_mfma_f32_16x16x32_bf16 v[196:199], v[94:97], v[98:101], v[196:199]
	v_max_i32_e32 v225, 0, v15
	v_fmac_f32_e32 v219, v225, v135
	s_cmp_lg_u32 s20, s22
	s_cbranch_scc0 .Lidx_flush_s1
	s_mov_b32 s4, s20
	s_branch .LBB0_935
.Lidx_flush_s1:
	s_nop 7
	v_max_i32_e32 v226, 0, v184
	v_fma_f32 v220, v226, v136, 0
	v_max_i32_e32 v227, 0, v185
	v_fmac_f32_e32 v220, v227, v137
	v_max_i32_e32 v226, 0, v186
	v_fmac_f32_e32 v220, v226, v138
	v_max_i32_e32 v227, 0, v187
	v_fmac_f32_e32 v220, v227, v139
	v_max_i32_e32 v226, 0, v192
	v_fmac_f32_e32 v220, v226, v140
	v_max_i32_e32 v227, 0, v193
	v_fmac_f32_e32 v220, v227, v141
	v_max_i32_e32 v226, 0, v194
	v_fmac_f32_e32 v220, v226, v142
	v_max_i32_e32 v227, 0, v195
	v_fmac_f32_e32 v220, v227, v143
	v_max_i32_e32 v226, 0, v188
	v_fma_f32 v221, v226, v136, 0
	v_max_i32_e32 v227, 0, v189
	v_fmac_f32_e32 v221, v227, v137
	v_max_i32_e32 v226, 0, v190
	v_fmac_f32_e32 v221, v226, v138
	v_max_i32_e32 v227, 0, v191
	v_fmac_f32_e32 v221, v227, v139
	v_max_i32_e32 v226, 0, v196
	v_fmac_f32_e32 v221, v226, v140
	v_max_i32_e32 v227, 0, v197
	v_fmac_f32_e32 v221, v227, v141
	v_max_i32_e32 v226, 0, v198
	v_fmac_f32_e32 v221, v226, v142
	v_max_i32_e32 v227, 0, v199
	v_fmac_f32_e32 v221, v227, v143
	s_nop 1
	v_permlane16_swap_b32_e32 v222, v223
	v_permlane16_swap_b32_e32 v218, v219
	v_permlane16_swap_b32_e32 v202, v203
	v_permlane16_swap_b32_e32 v220, v221
	v_add_f32_e32 v222, v222, v223
	v_add_f32_e32 v218, v218, v219
	v_add_f32_e32 v202, v202, v203
	v_add_f32_e32 v220, v220, v221
	s_nop 1
	v_permlane32_swap_b32_e32 v222, v218
	v_permlane32_swap_b32_e32 v202, v220
	v_add_f32_e32 v222, v222, v218
	v_add_f32_e32 v202, v202, v220
	global_store_dword v[228:229], v222, off offset:256 nt
	global_store_dword v[230:231], v202, off offset:256 nt
	s_branch .LBB0_916
